# v92 + w_in epilogue: packed f32 VALU ops (v_pk_fma/mul/add_f32) replaced by scalar pairs
# speedup vs baseline: 1.0062x; 1.0062x over previous
;     __device__ __forceinline__ void operator()(const f32x4 (&acc)[2][2][4][2], const Unit& u, int wr, int wc, int fr, int fq) const {
;     ...
;         f32x4 bv[2][2];
; #pragma unroll
;         for (int bj = 0; bj < 2; ++bj)
; #pragma unroll
;             for (int n = 0; n < 2; ++n) bv[bj][n] = *(const f32x4*)(bias + (size_t)b * nbias + col0 + bj * HALF + 4 * n);
;         float rsv[2][4];
;         { f32x4 pq[2][4];
; #pragma unroll
;           for (int ai = 0; ai < 2; ++ai)
; #pragma unroll
;               for (int m = 0; m < 4; ++m) pq[ai][m] = *(const f32x4*)(ssq + (size_t)(row0 + ai * HALF + m * 16) * 16 + 4 * fq);
; #pragma unroll
;           for (int ai = 0; ai < 2; ++ai)
; #pragma unroll
;               for (int m = 0; m < 4; ++m) { float t = (pq[ai][m][0] + pq[ai][m][1]) + (pq[ai][m][2] + pq[ai][m][3]); t += __shfl_xor(t, 16); t += __shfl_xor(t, 32);
;                   rsv[ai][m] = rsqrtf(t * (1.f / DM) + EPS); } }
; #pragma unroll
;         for (int ai = 0; ai < 2; ++ai)
; #pragma unroll
;             for (int m = 0; m < 4; ++m) { const int row = row0 + ai * HALF + m * 16; bf16_t* rowp = O + (size_t)row * ldc + col0; float s = 0.f, q = 0.f;
;                 const float rstd = rsv[ai][m];
; #pragma unroll
;                 for (int bj = 0; bj < 2; ++bj) { f32x4 v0 = acc[ai][bj][m][0] * rstd + bv[bj][0], v1 = acc[ai][bj][m][1] * rstd + bv[bj][1];
;                     if (ACT == 1) {
; #pragma unroll
;                         for (int e = 0; e < 4; ++e) { const float a = fmaxf(v0[e], 0.f), b2 = fmaxf(v1[e], 0.f); v0[e] = a * a; v1[e] = b2 * b2; } }
;                     if (ACT == 2) {
; #pragma unroll
;                         for (int e = 0; e < 4; ++e) { v0[e] = gelu_tanh(v0[e]); v1[e] = gelu_tanh(v1[e]); s += v0[e] + v1[e]; q += v0[e] * v0[e] + v1[e] * v1[e]; } }
.LBB0_186:
	s_min_i32 s15, s36, 64
	s_ashr_i32 s16, s15, 5
	s_ashr_i32 s17, s16, 31
	s_lshl_b64 s[16:17], s[16:17], 14
	v_lshl_add_u32 v196, s36, 8, v201
	v_lshl_or_b32 v182, s44, 8, v203
	s_add_u32 s16, s62, s16
	v_ashrrev_i32_e32 v197, 31, v196
	s_addc_u32 s17, s63, s17
	v_ashrrev_i32_e32 v183, 31, v182
	v_lshlrev_b64 v[144:145], 6, v[196:197]
	v_or_b32_e32 v194, 16, v196
	v_lshl_add_u64 v[36:37], v[182:183], 2, s[16:17]
	v_lshl_add_u64 v[144:145], v[174:175], 0, v[144:145]
	v_ashrrev_i32_e32 v195, 31, v194
	global_load_dwordx4 v[40:43], v[36:37], off offset:16
	global_load_dwordx4 v[44:47], v[36:37], off
	global_load_dwordx4 v[32:35], v[36:37], off offset:528
	s_nop 0
	global_load_dwordx4 v[36:39], v[36:37], off offset:512
	v_or_b32_e32 v192, 32, v196
	global_load_dwordx4 v[208:211], v[144:145], off
	v_lshlrev_b64 v[144:145], 6, v[194:195]
	v_lshl_add_u64 v[144:145], v[174:175], 0, v[144:145]
	global_load_dwordx4 v[220:223], v[144:145], off
	v_ashrrev_i32_e32 v193, 31, v192
	v_lshlrev_b64 v[144:145], 6, v[192:193]
	v_or_b32_e32 v190, 48, v196
	v_lshl_add_u64 v[144:145], v[174:175], 0, v[144:145]
	v_ashrrev_i32_e32 v191, 31, v190
	global_load_dwordx4 v[160:163], v[144:145], off
	v_lshlrev_b64 v[144:145], 6, v[190:191]
	v_add_u32_e32 v188, 0x80, v196
	v_lshl_add_u64 v[144:145], v[174:175], 0, v[144:145]
	v_ashrrev_i32_e32 v189, 31, v188
	global_load_dwordx4 v[164:167], v[144:145], off
	v_lshlrev_b64 v[144:145], 6, v[188:189]
	v_add_u32_e32 v186, 0x90, v196
	v_lshl_add_u64 v[144:145], v[174:175], 0, v[144:145]
	v_ashrrev_i32_e32 v187, 31, v186
	global_load_dwordx4 v[156:159], v[144:145], off
	v_lshlrev_b64 v[144:145], 6, v[186:187]
	v_add_u32_e32 v184, 0xa0, v196
	v_lshl_add_u64 v[144:145], v[174:175], 0, v[144:145]
	v_ashrrev_i32_e32 v185, 31, v184
	global_load_dwordx4 v[152:155], v[144:145], off
	v_lshlrev_b64 v[144:145], 6, v[184:185]
	v_add_u32_e32 v180, 0xb0, v196
	v_lshl_add_u64 v[144:145], v[174:175], 0, v[144:145]
	v_ashrrev_i32_e32 v181, 31, v180
	global_load_dwordx4 v[148:151], v[144:145], off
	v_lshlrev_b64 v[144:145], 6, v[180:181]
	v_lshl_add_u64 v[144:145], v[174:175], 0, v[144:145]
	global_load_dwordx4 v[144:147], v[144:145], off
	v_and_b32_e32 v199, 64, v246
	v_xor_b32_e32 v198, 16, v246
	v_add_u32_e32 v199, 64, v199
	v_cmp_lt_i32_e32 vcc, v198, v199
	s_mov_b32 s16, 0x3a800000
	s_cmp_gt_i32 s44, 7
	v_cndmask_b32_e32 v198, v246, v198, vcc
	v_lshlrev_b32_e32 v205, 2, v198
	v_xor_b32_e32 v198, 32, v246
	v_cmp_lt_i32_e32 vcc, v198, v199
	s_cselect_b64 s[46:47], -1, 0
	s_lshl_b32 s15, s44, 2
	v_cndmask_b32_e32 v198, v246, v198, vcc
	v_lshlrev_b32_e32 v206, 2, v198
	s_waitcnt vmcnt(0)
	v_mov_b32_e32 v198, v209
	v_mov_b32_e32 v199, v210
	v_mov_b32_e32 v209, v211
	v_add_f32_e32 v198, v198, v208
	v_add_f32_e32 v199, v199, v209
	v_mov_b32_e32 v208, v221
	v_mov_b32_e32 v209, v222
	v_mov_b32_e32 v221, v223
	v_add_f32_e32 v208, v208, v220
	v_add_f32_e32 v209, v209, v221
	v_mov_b32_e32 v211, v198
	v_mov_b32_e32 v210, v208
	v_mov_b32_e32 v198, v209
	v_add_f32_e32 v198, v210, v198
	v_add_f32_e32 v199, v211, v199
	ds_bpermute_b32 v209, v205, v199
	ds_bpermute_b32 v208, v205, v198
	s_waitcnt lgkmcnt(0)
	v_add_f32_e32 v198, v198, v208
	v_add_f32_e32 v199, v199, v209
	ds_bpermute_b32 v209, v206, v199
	ds_bpermute_b32 v208, v206, v198
	s_waitcnt lgkmcnt(0)
	v_add_f32_e32 v198, v198, v208
	v_add_f32_e32 v199, v199, v209
	s_nop 0
	v_fma_f32 v198, v198, s16, v214
	v_fma_f32 v199, v199, s16, v214
	v_mov_b32_e32 v208, v161
	v_mul_f32_e32 v200, 0x4b800000, v199
	v_cmp_gt_f32_e64 s[42:43], s27, v199
	v_mov_b32_e32 v209, v162
	v_mov_b32_e32 v161, v163
	v_cndmask_b32_e64 v199, v199, v200, s[42:43]
	v_mov_b32_e32 v162, v165
	v_mov_b32_e32 v163, v166
	v_mov_b32_e32 v165, v167
	v_rsq_f32_e32 v199, v199
	v_add_f32_e32 v160, v208, v160
	v_add_f32_e32 v161, v209, v161
	v_add_f32_e32 v162, v162, v164
	v_add_f32_e32 v163, v163, v165
	v_mov_b32_e32 v165, v160
	v_mov_b32_e32 v164, v162
	v_mov_b32_e32 v160, v163
	v_add_f32_e32 v160, v164, v160
	v_add_f32_e32 v161, v165, v161
	v_mov_b32_e32 v164, v157
	v_mov_b32_e32 v165, v158
	v_mov_b32_e32 v157, v159
	v_mov_b32_e32 v158, v153
	v_mov_b32_e32 v159, v154
	v_mov_b32_e32 v153, v155
	v_add_f32_e32 v156, v164, v156
	v_add_f32_e32 v157, v165, v157
	v_add_f32_e32 v152, v158, v152
	v_add_f32_e32 v153, v159, v153
	v_mul_f32_e32 v200, 0x45800000, v199
	v_mov_b32_e32 v154, v152
	v_mov_b32_e32 v155, v156
	v_mov_b32_e32 v156, v153
	v_cndmask_b32_e64 v200, v199, v200, s[42:43]
	v_add_f32_e32 v152, v154, v156
	v_add_f32_e32 v153, v155, v157
	v_mov_b32_e32 v156, v149
	v_mov_b32_e32 v157, v150
	v_mov_b32_e32 v149, v151
	v_mov_b32_e32 v150, v145
	v_mov_b32_e32 v151, v146
	v_mov_b32_e32 v145, v147
	v_add_f32_e32 v144, v150, v144
	v_add_f32_e32 v145, v151, v145
	v_fma_f32 v150, v138, v200, v42
	v_fma_f32 v151, v139, v200, v43
	v_fma_f32 v138, v136, v200, v40
	v_fma_f32 v139, v137, v200, v41
	v_fma_f32 v140, v140, v200, v44
	v_fma_f32 v141, v141, v200, v45
	v_mul_f32_e32 v137, 0x3d122279, v138
	v_fmaak_f32 v137, v138, v137, 0x3f4c422a
	v_mul_f32_e32 v137, v138, v137
	v_mul_f32_e32 v137, 0x4038aa3b, v137
	v_exp_f32_e32 v137, v137
	v_add_f32_e32 v148, v156, v148
	v_add_f32_e32 v149, v157, v149
	v_mul_f32_e32 v136, 0x3d122279, v140
	v_fmaak_f32 v136, v140, v136, 0x3f4c422a
	v_add_f32_e32 v137, 1.0, v137
	v_rcp_f32_e32 v156, v137
	v_mul_f32_e32 v137, 0x3d122279, v141
	v_fmaak_f32 v137, v141, v137, 0x3f4c422a
	v_mul_f32_e32 v136, v140, v136
	v_mul_f32_e32 v137, v141, v137
	v_mul_f32_e32 v136, 0x4038aa3b, v136
	v_mul_f32_e32 v137, 0x4038aa3b, v137
	v_exp_f32_e32 v136, v136
	v_exp_f32_e32 v137, v137
	v_mul_f32_e32 v157, 0x3d122279, v139
; __device__ __forceinline__ unsigned cvt_pk_bf16(float lo, float hi) { unsigned r; asm volatile("v_cvt_pk_bf16_f32 %0, %1, %2" : "=v"(r) : "v"(lo), "v"(hi)); return r; }
;     __device__ __forceinline__ void operator()(const f32x4 (&acc)[2][2][4][2], const Unit& u, int wr, int wc, int fr, int fq) const {
;     ...
;             for (int m = 0; m < 4; ++m) { const int row = row0 + ai * HALF + m * 16; bf16_t* rowp = O + (size_t)row * ldc + col0; float s = 0.f, q = 0.f;
;                 const float rstd = rsv[ai][m];
; #pragma unroll
;                 for (int bj = 0; bj < 2; ++bj) { f32x4 v0 = acc[ai][bj][m][0] * rstd + bv[bj][0], v1 = acc[ai][bj][m][1] * rstd + bv[bj][1];
;                     if (ACT == 1) {
; #pragma unroll
;                         for (int e = 0; e < 4; ++e) { const float a = fmaxf(v0[e], 0.f), b2 = fmaxf(v1[e], 0.f); v0[e] = a * a; v1[e] = b2 * b2; } }
;                     if (ACT == 2) {
; #pragma unroll
;                         for (int e = 0; e < 4; ++e) { v0[e] = gelu_tanh(v0[e]); v1[e] = gelu_tanh(v1[e]); s += v0[e] + v1[e]; q += v0[e] * v0[e] + v1[e] * v1[e]; } }
;                     u32x4 w; w.x = cvt_pk_bf16(v0[0], v0[1]); w.y = cvt_pk_bf16(v0[2], v0[3]); w.z = cvt_pk_bf16(v1[0], v1[1]); w.w = cvt_pk_bf16(v1[2], v1[3]);
;                     *(u32x4*)(rowp + bj * HALF) = w; }
	v_fmaak_f32 v157, v139, v157, 0x3f4c422a
	v_add_f32_e32 v136, 1.0, v136
	v_add_f32_e32 v137, 1.0, v137
	v_rcp_f32_e32 v136, v136
	v_rcp_f32_e32 v137, v137
	v_mul_f32_e32 v157, v139, v157
	v_mul_f32_e32 v157, 0x4038aa3b, v157
	v_exp_f32_e32 v157, v157
	v_fma_f32 v136, -v140, v136, v140
	v_fma_f32 v137, -v141, v137, v141
	v_mul_f32_e32 v141, 0x3d122279, v150
	v_fmaak_f32 v141, v150, v141, 0x3f4c422a
	v_mul_f32_e32 v141, v150, v141
	v_mul_f32_e32 v141, 0x4038aa3b, v141
	v_add_f32_e32 v157, 1.0, v157
	v_exp_f32_e32 v141, v141
	v_rcp_f32_e32 v157, v157
	v_fma_f32 v142, v142, v200, v46
	v_fma_f32 v143, v143, v200, v47
	v_mov_b32_e32 v146, v144
	v_add_f32_e32 v141, 1.0, v141
	v_fma_f32 v138, -v138, v156, v138
	v_fma_f32 v139, -v139, v157, v139
	v_mul_f32_e32 v140, 0x3d122279, v142
	v_rcp_f32_e32 v156, v141
	v_mul_f32_e32 v141, 0x3d122279, v143
	v_mul_f32_e32 v157, 0x3d122279, v151
	v_fmaak_f32 v140, v142, v140, 0x3f4c422a
	v_fmaak_f32 v141, v143, v141, 0x3f4c422a
	v_fmaak_f32 v157, v151, v157, 0x3f4c422a
	v_mul_f32_e32 v140, v142, v140
	v_mul_f32_e32 v141, v143, v141
	v_mul_f32_e32 v157, v151, v157
	v_mul_f32_e32 v140, 0x4038aa3b, v140
	v_mul_f32_e32 v141, 0x4038aa3b, v141
	v_mul_f32_e32 v157, 0x4038aa3b, v157
	v_exp_f32_e32 v140, v140
	v_exp_f32_e32 v141, v141
	v_exp_f32_e32 v157, v157
	v_mov_b32_e32 v147, v148
	v_add_f32_e32 v140, 1.0, v140
	v_add_f32_e32 v141, 1.0, v141
	v_add_f32_e32 v157, 1.0, v157
	v_rcp_f32_e32 v140, v140
	v_rcp_f32_e32 v141, v141
	v_rcp_f32_e32 v157, v157
	v_mov_b32_e32 v148, v145
	v_add_f32_e32 v144, v146, v148
	v_add_f32_e32 v145, v147, v149
	v_fma_f32 v140, -v142, v140, v142
	v_fma_f32 v141, -v143, v141, v143
	v_fma_f32 v142, -v150, v156, v150
	v_fma_f32 v143, -v151, v157, v151
	v_fma_f32 v150, v130, v200, v34
	v_fma_f32 v151, v131, v200, v35
	v_fma_f32 v130, v128, v200, v32
	v_fma_f32 v131, v129, v200, v33
	v_lshlrev_b64 v[148:149], 13, v[196:197]
	v_mul_f32_e32 v129, 0x3d122279, v130
	v_fmaak_f32 v129, v130, v129, 0x3f4c422a
	v_mul_f32_e32 v129, v130, v129
	v_mul_f32_e32 v129, 0x4038aa3b, v129
	v_exp_f32_e32 v129, v129
	v_lshl_add_u64 v[148:149], s[2:3], 0, v[148:149]
	v_lshl_add_u64 v[148:149], v[182:183], 1, v[148:149]
	v_cvt_pk_bf16_f32 v156, v136, v137
	v_fma_f32 v132, v132, v200, v36
	v_fma_f32 v133, v133, v200, v37
	v_add_f32_e32 v129, 1.0, v129
	v_cvt_pk_bf16_f32 v157, v140, v141
	v_cvt_pk_bf16_f32 v158, v138, v139
	v_cvt_pk_bf16_f32 v159, v142, v143
	global_store_dwordx4 v[148:149], v[156:159], off sc1
	v_mul_f32_e32 v128, 0x3d122279, v132
	v_fmaak_f32 v128, v132, v128, 0x3f4c422a
	v_rcp_f32_e32 v156, v129
	v_mul_f32_e32 v129, 0x3d122279, v133
	v_fmaak_f32 v129, v133, v129, 0x3f4c422a
	v_mul_f32_e32 v128, v132, v128
	v_mul_f32_e32 v129, v133, v129
	v_mul_f32_e32 v128, 0x4038aa3b, v128
	v_mul_f32_e32 v129, 0x4038aa3b, v129
	v_exp_f32_e32 v128, v128
	v_exp_f32_e32 v129, v129
	v_mul_f32_e32 v157, 0x3d122279, v131
	v_fmaak_f32 v157, v131, v157, 0x3f4c422a
	v_add_f32_e32 v128, 1.0, v128
	v_add_f32_e32 v129, 1.0, v129
	v_rcp_f32_e32 v128, v128
	v_rcp_f32_e32 v129, v129
	v_mul_f32_e32 v157, v131, v157
	v_mul_f32_e32 v157, 0x4038aa3b, v157
	v_exp_f32_e32 v157, v157
	v_fma_f32 v128, -v132, v128, v132
	v_fma_f32 v129, -v133, v129, v133
	v_mul_f32_e32 v133, 0x3d122279, v150
	v_fmaak_f32 v133, v150, v133, 0x3f4c422a
	v_mul_f32_e32 v133, v150, v133
	v_mul_f32_e32 v133, 0x4038aa3b, v133
	v_add_f32_e32 v157, 1.0, v157
	v_exp_f32_e32 v133, v133
	v_rcp_f32_e32 v157, v157
	v_fma_f32 v134, v134, v200, v38
	v_fma_f32 v135, v135, v200, v39
	v_mov_b32_e32 v158, v150
	v_add_f32_e32 v133, 1.0, v133
	v_fma_f32 v130, -v130, v156, v130
	v_fma_f32 v131, -v131, v157, v131
	v_rcp_f32_e32 v156, v133
	v_mul_f32_e32 v133, 0x3d122279, v135
	v_mul_f32_e32 v132, 0x3d122279, v134
	v_fmaak_f32 v133, v135, v133, 0x3f4c422a
	v_mul_f32_e32 v150, 0x3d122279, v151
	v_fmaak_f32 v132, v134, v132, 0x3f4c422a
	v_mul_f32_e32 v133, v135, v133
	v_fmaak_f32 v150, v151, v150, 0x3f4c422a
	v_mul_f32_e32 v132, v134, v132
	v_mul_f32_e32 v133, 0x4038aa3b, v133
	v_mul_f32_e32 v150, v151, v150
	ds_bpermute_b32 v163, v205, v161
	ds_bpermute_b32 v162, v205, v160
	ds_bpermute_b32 v155, v205, v153
	ds_bpermute_b32 v154, v205, v152
	ds_bpermute_b32 v147, v205, v145
	ds_bpermute_b32 v146, v205, v144
	v_mul_f32_e32 v132, 0x4038aa3b, v132
	v_exp_f32_e32 v133, v133
	v_mul_f32_e32 v150, 0x4038aa3b, v150
	v_exp_f32_e32 v132, v132
	v_exp_f32_e32 v150, v150
	v_add_f32_e32 v133, 1.0, v133
	s_waitcnt lgkmcnt(4)
	v_add_f32_e32 v160, v160, v162
	v_add_f32_e32 v161, v161, v163
	s_waitcnt lgkmcnt(2)
	v_add_f32_e32 v152, v152, v154
	v_add_f32_e32 v153, v153, v155
	s_waitcnt lgkmcnt(0)
	v_add_f32_e32 v144, v144, v146
	v_add_f32_e32 v145, v145, v147
	v_add_f32_e32 v132, 1.0, v132
	v_rcp_f32_e32 v133, v133
	v_add_f32_e32 v150, 1.0, v150
	ds_bpermute_b32 v163, v206, v161
	ds_bpermute_b32 v162, v206, v160
	ds_bpermute_b32 v155, v206, v153
	ds_bpermute_b32 v154, v206, v152
	ds_bpermute_b32 v147, v206, v145
	ds_bpermute_b32 v146, v206, v144
	v_rcp_f32_e32 v132, v132
	v_rcp_f32_e32 v150, v150
	s_sub_i32 s16, s15, 32
	s_ashr_i32 s17, s16, 31
	s_or_b64 s[36:37], s[16:17], s[8:9]
	v_mov_b32_e32 v159, v135
	v_mov_b32_e32 v157, v133
	v_cmp_gt_f32_e32 vcc, s27, v198
	s_cmp_lt_i32 s44, 8
	v_fma_f32 v132, -v134, v132, v134
	v_fma_f32 v133, -v135, v133, v135
	v_fma_f32 v134, -v158, v156, v158
	v_fma_f32 v135, -v159, v157, v159
	v_fma_f32 v150, -v151, v150, v151
	v_cvt_pk_bf16_f32 v156, v128, v129
	v_cvt_pk_bf16_f32 v157, v132, v133
	v_cvt_pk_bf16_f32 v158, v130, v131
	v_cvt_pk_bf16_f32 v159, v134, v150
	global_store_dwordx4 v[148:149], v[156:159], off offset:256 sc1
	s_cbranch_scc1 .LBB0_190
; __device__ __forceinline__ unsigned cvt_pk_bf16(float lo, float hi) { unsigned r; asm volatile("v_cvt_pk_bf16_f32 %0, %1, %2" : "=v"(r) : "v"(lo), "v"(hi)); return r; }
;     __device__ __forceinline__ void operator()(const f32x4 (&acc)[2][2][4][2], const Unit& u, int wr, int wc, int fr, int fq) const {
;     ...
;                         for (int e = 0; e < 4; ++e) { v0[e] = gelu_tanh(v0[e]); v1[e] = gelu_tanh(v1[e]); s += v0[e] + v1[e]; q += v0[e] * v0[e] + v1[e] * v1[e]; } }
;                     u32x4 w; w.x = cvt_pk_bf16(v0[0], v0[1]); w.y = cvt_pk_bf16(v0[2], v0[3]); w.z = cvt_pk_bf16(v1[0], v1[1]); w.w = cvt_pk_bf16(v1[2], v1[3]);
;                     *(u32x4*)(rowp + bj * HALF) = w; }
;                 if (ACT == 2) { if (u.pn >= 8) { s += __shfl_xor(s, 16); s += __shfl_xor(s, 32); q += __shfl_xor(q, 16); q += __shfl_xor(q, 32);
;                     if (fq == 0) *(f32x2*)(stats + ((size_t)row * 32 + (u.pn - 8) * 4 + wc) * 2) = (f32x2){s, q}; } }
	v_mul_f32_e32 v148, v138, v138
	v_mul_f32_e32 v149, v139, v139
	v_mul_f32_e32 v156, v142, v142
	v_mul_f32_e32 v157, v143, v143
	v_fma_f32 v148, v136, v136, v148
	v_fma_f32 v149, v137, v137, v149
	v_fma_f32 v156, v140, v140, v156
	v_fma_f32 v157, v141, v141, v157
	v_add_f32_e32 v148, v148, v149
	v_mul_f32_e32 v158, v130, v130
	v_mul_f32_e32 v159, v131, v131
	v_add_f32_e32 v148, v156, v148
	v_fma_f32 v158, v128, v128, v158
	v_fma_f32 v159, v129, v129, v159
	v_add_f32_e32 v148, v157, v148
	v_add_f32_e32 v148, v158, v148
	v_add_f32_e32 v149, v159, v148
	v_add_f32_e32 v148, v158, v148
	v_add_f32_e32 v136, v136, v138
	v_add_f32_e32 v137, v137, v139
	v_mov_b32_e32 v156, v132
	v_mov_b32_e32 v157, v134
	v_mul_f32_e32 v148, v132, v132
	v_add_f32_e32 v158, v132, v134
	v_add_f32_e32 v159, v133, v135
	v_mul_f32_e32 v134, v132, v134
	v_mul_f32_e32 v135, v133, v135
	v_add_f32_e32 v132, 0, v136
	v_add_f32_e32 v132, v137, v132
	v_add_f32_e32 v136, v140, v142
	v_add_f32_e32 v137, v141, v143
	v_add_f32_e32 v128, v128, v130
	v_add_f32_e32 v129, v129, v131
	v_add_f32_e32 v132, v136, v132
	v_add_f32_e32 v132, v137, v132
	v_fma_f32 v156, v156, v156, v148
	v_fma_f32 v157, v157, v157, v148
	v_add_f32_e32 v128, v128, v132
	v_mov_b32_e32 v159, v135
	v_mul_f32_e32 v135, v150, v150
	v_add_f32_e32 v134, v129, v128
	v_mov_b32_e32 v156, v133
	v_mov_b32_e32 v151, v149
	v_add_f32_e32 v128, v158, v134
	v_add_f32_e32 v129, v159, v135
	v_add_f32_e32 v130, v156, v150
	v_add_f32_e32 v131, v157, v151
	s_nop 0
	v_add_f32_e32 v128, v128, v130
	v_add_f32_e32 v129, v129, v131
	ds_bpermute_b32 v130, v205, v128
	ds_bpermute_b32 v131, v205, v129
	s_waitcnt lgkmcnt(0)
	v_add_f32_e32 v128, v128, v130
	v_add_f32_e32 v129, v129, v131
	ds_bpermute_b32 v130, v206, v128
	ds_bpermute_b32 v131, v206, v129
	s_and_saveexec_b64 s[42:43], s[38:39]
	s_cbranch_execz .LBB0_189
	v_lshlrev_b64 v[132:133], 8, v[196:197]
	s_waitcnt lgkmcnt(0)
	v_add_f32_e32 v128, v128, v130
	v_add_f32_e32 v129, v129, v131
	v_lshl_add_u64 v[130:131], s[6:7], 0, v[132:133]
	v_lshl_add_u64 v[130:131], s[36:37], 3, v[130:131]
	global_store_dwordx2 v[130:131], v[128:129], off

; __device__ __forceinline__ unsigned cvt_pk_bf16(float lo, float hi) { unsigned r; asm volatile("v_cvt_pk_bf16_f32 %0, %1, %2" : "=v"(r) : "v"(lo), "v"(hi)); return r; }
; __device__ __forceinline__ float gelu_tanh(float x) {
;     const float u = x * (0.7978845608f + 0.0356774081f * x * x);
;     const float e = __builtin_amdgcn_exp2f(u * 2.8853900818f);
;     return x - x * __builtin_amdgcn_rcpf(e + 1.0f);
; }
;     __device__ __forceinline__ void operator()(const f32x4 (&acc)[2][2][4][2], const Unit& u, int wr, int wc, int fr, int fq) const {
;     ...
;                 for (int bj = 0; bj < 2; ++bj) { f32x4 v0 = acc[ai][bj][m][0] * rstd + bv[bj][0], v1 = acc[ai][bj][m][1] * rstd + bv[bj][1];
;                     if (ACT == 1) {
; #pragma unroll
;                         for (int e = 0; e < 4; ++e) { const float a = fmaxf(v0[e], 0.f), b2 = fmaxf(v1[e], 0.f); v0[e] = a * a; v1[e] = b2 * b2; } }
;                     if (ACT == 2) {
; #pragma unroll
;                         for (int e = 0; e < 4; ++e) { v0[e] = gelu_tanh(v0[e]); v1[e] = gelu_tanh(v1[e]); s += v0[e] + v1[e]; q += v0[e] * v0[e] + v1[e] * v1[e]; } }
;                     u32x4 w; w.x = cvt_pk_bf16(v0[0], v0[1]); w.y = cvt_pk_bf16(v0[2], v0[3]); w.z = cvt_pk_bf16(v1[0], v1[1]); w.w = cvt_pk_bf16(v1[2], v1[3]);
;                     *(u32x4*)(rowp + bj * HALF) = w; }
.LBB0_190:
	v_mul_f32_e32 v128, 0x4b800000, v198
	v_cndmask_b32_e32 v128, v198, v128, vcc
	v_rsq_f32_e32 v128, v128
	s_nop 0
	v_mul_f32_e32 v129, 0x45800000, v128
	v_cndmask_b32_e32 v134, v128, v129, vcc
	s_waitcnt lgkmcnt(0)
	v_fma_f32 v130, v122, v134, v42
	v_fma_f32 v131, v123, v134, v43
	v_fma_f32 v122, v120, v134, v40
	v_fma_f32 v123, v121, v134, v41
	v_fma_f32 v124, v124, v134, v44
	v_fma_f32 v125, v125, v134, v45
	v_mul_f32_e32 v121, 0x3d122279, v122
	v_fmaak_f32 v121, v122, v121, 0x3f4c422a
	v_mul_f32_e32 v121, v122, v121
	v_mul_f32_e32 v121, 0x4038aa3b, v121
	v_exp_f32_e32 v121, v121
	v_mul_f32_e32 v120, 0x3d122279, v124
	v_fmaak_f32 v120, v124, v120, 0x3f4c422a
	v_mul_f32_e32 v120, v124, v120
	v_add_f32_e32 v121, 1.0, v121
	v_rcp_f32_e32 v132, v121
	v_mul_f32_e32 v121, 0x3d122279, v125
	v_fmaak_f32 v121, v125, v121, 0x3f4c422a
	v_mul_f32_e32 v121, v125, v121
	v_mul_f32_e32 v120, 0x4038aa3b, v120
	v_mul_f32_e32 v121, 0x4038aa3b, v121
	v_exp_f32_e32 v120, v120
	v_exp_f32_e32 v121, v121
	v_mul_f32_e32 v133, 0x3d122279, v123
	v_fmaak_f32 v133, v123, v133, 0x3f4c422a
	v_add_f32_e32 v120, 1.0, v120
	v_add_f32_e32 v121, 1.0, v121
	v_rcp_f32_e32 v120, v120
	v_rcp_f32_e32 v121, v121
	v_mul_f32_e32 v133, v123, v133
	v_mul_f32_e32 v133, 0x4038aa3b, v133
	v_exp_f32_e32 v133, v133
	v_fma_f32 v120, -v124, v120, v124
	v_fma_f32 v121, -v125, v121, v125
	v_mul_f32_e32 v125, 0x3d122279, v130
	v_fmaak_f32 v125, v130, v125, 0x3f4c422a
	v_mul_f32_e32 v125, v130, v125
	v_mul_f32_e32 v125, 0x4038aa3b, v125
	v_add_f32_e32 v133, 1.0, v133
	v_exp_f32_e32 v125, v125
	v_rcp_f32_e32 v133, v133
	v_fma_f32 v126, v126, v134, v46
	v_fma_f32 v127, v127, v134, v47
	v_lshlrev_b64 v[128:129], 13, v[194:195]
	v_add_f32_e32 v125, 1.0, v125
	v_fma_f32 v122, -v122, v132, v122
	v_fma_f32 v123, -v123, v133, v123
	v_mul_f32_e32 v124, 0x3d122279, v126
	v_rcp_f32_e32 v132, v125
	v_mul_f32_e32 v125, 0x3d122279, v127
	v_mul_f32_e32 v133, 0x3d122279, v131
	v_fmaak_f32 v124, v126, v124, 0x3f4c422a
	v_fmaak_f32 v125, v127, v125, 0x3f4c422a
	v_fmaak_f32 v133, v131, v133, 0x3f4c422a
	v_mul_f32_e32 v124, v126, v124
	v_mul_f32_e32 v125, v127, v125
	v_mul_f32_e32 v133, v131, v133
	v_mul_f32_e32 v124, 0x4038aa3b, v124
	v_mul_f32_e32 v125, 0x4038aa3b, v125
	v_mul_f32_e32 v133, 0x4038aa3b, v133
	v_exp_f32_e32 v124, v124
	v_exp_f32_e32 v125, v125
	v_exp_f32_e32 v133, v133
	v_lshl_add_u64 v[128:129], s[2:3], 0, v[128:129]
	v_add_f32_e32 v124, 1.0, v124
	v_add_f32_e32 v125, 1.0, v125
	v_add_f32_e32 v133, 1.0, v133
	v_rcp_f32_e32 v124, v124
	v_rcp_f32_e32 v125, v125
	v_rcp_f32_e32 v133, v133
	v_lshl_add_u64 v[128:129], v[182:183], 1, v[128:129]
	v_fma_f32 v116, v116, v134, v36
	v_fma_f32 v117, v117, v134, v37
	v_fma_f32 v124, -v126, v124, v126
	v_fma_f32 v125, -v127, v125, v127
	v_fma_f32 v126, -v130, v132, v130
	v_fma_f32 v127, -v131, v133, v131
	v_cvt_pk_bf16_f32 v130, v120, v121
	v_cvt_pk_bf16_f32 v131, v124, v125
	v_cvt_pk_bf16_f32 v132, v122, v123
	v_fma_f32 v118, v118, v134, v38
	v_fma_f32 v119, v119, v134, v39
	v_cvt_pk_bf16_f32 v133, v126, v127
	global_store_dwordx4 v[128:129], v[130:133], off sc1
	s_andn2_b64 vcc, exec, s[46:47]
	s_nop 0
	v_fma_f32 v130, v114, v134, v34
	v_fma_f32 v131, v115, v134, v35
	v_fma_f32 v114, v112, v134, v32
	v_fma_f32 v115, v113, v134, v33
	v_mul_f32_e32 v112, 0x3d122279, v116
	v_mul_f32_e32 v113, 0x3d122279, v114
	v_fmaak_f32 v113, v114, v113, 0x3f4c422a
	v_mul_f32_e32 v113, v114, v113
	v_mul_f32_e32 v113, 0x4038aa3b, v113
	v_exp_f32_e32 v113, v113
	v_fmaak_f32 v112, v116, v112, 0x3f4c422a
	v_mul_f32_e32 v112, v116, v112
	v_mul_f32_e32 v112, 0x4038aa3b, v112
	v_add_f32_e32 v113, 1.0, v113
	v_rcp_f32_e32 v132, v113
	v_mul_f32_e32 v113, 0x3d122279, v117
	v_fmaak_f32 v113, v117, v113, 0x3f4c422a
	v_mul_f32_e32 v113, v117, v113
	v_mul_f32_e32 v113, 0x4038aa3b, v113
	v_exp_f32_e32 v112, v112
	v_exp_f32_e32 v113, v113
	v_mul_f32_e32 v133, 0x3d122279, v115
	v_fmaak_f32 v133, v115, v133, 0x3f4c422a
	v_add_f32_e32 v112, 1.0, v112
	v_add_f32_e32 v113, 1.0, v113
	v_rcp_f32_e32 v112, v112
	v_rcp_f32_e32 v113, v113
	v_mul_f32_e32 v133, v115, v133
	v_mul_f32_e32 v133, 0x4038aa3b, v133
	v_exp_f32_e32 v133, v133
	v_fma_f32 v112, -v116, v112, v116
	v_fma_f32 v113, -v117, v113, v117
	v_mul_f32_e32 v117, 0x3d122279, v130
	v_fmaak_f32 v117, v130, v117, 0x3f4c422a
	v_mul_f32_e32 v117, v130, v117
	v_mul_f32_e32 v117, 0x4038aa3b, v117
	v_add_f32_e32 v133, 1.0, v133
	v_exp_f32_e32 v117, v117
	v_rcp_f32_e32 v133, v133
	v_mul_f32_e32 v116, 0x3d122279, v118
	v_mov_b32_e32 v134, v130
	v_add_f32_e32 v117, 1.0, v117
	v_fma_f32 v114, -v114, v132, v114
	v_fma_f32 v115, -v115, v133, v115
	v_rcp_f32_e32 v132, v117
	v_mul_f32_e32 v117, 0x3d122279, v119
	v_fmaak_f32 v117, v119, v117, 0x3f4c422a
	v_mul_f32_e32 v130, 0x3d122279, v131
	v_fmaak_f32 v116, v118, v116, 0x3f4c422a
	v_mul_f32_e32 v117, v119, v117
	v_fmaak_f32 v130, v131, v130, 0x3f4c422a
	v_mul_f32_e32 v116, v118, v116
	v_mul_f32_e32 v117, 0x4038aa3b, v117
	v_mul_f32_e32 v130, v131, v130
	v_mul_f32_e32 v116, 0x4038aa3b, v116
	v_exp_f32_e32 v117, v117
	v_mul_f32_e32 v130, 0x4038aa3b, v130
	v_exp_f32_e32 v116, v116
	v_exp_f32_e32 v130, v130
	v_add_f32_e32 v117, 1.0, v117
	v_rcp_f32_e32 v117, v117
	v_add_f32_e32 v116, 1.0, v116
	v_add_f32_e32 v130, 1.0, v130
	v_rcp_f32_e32 v116, v116
	v_rcp_f32_e32 v130, v130
	v_mov_b32_e32 v135, v119
	v_mov_b32_e32 v133, v117
	v_fma_f32 v116, -v118, v116, v118
	v_fma_f32 v117, -v119, v117, v119
	v_fma_f32 v118, -v134, v132, v134
	v_fma_f32 v119, -v135, v133, v135
	v_fma_f32 v130, -v131, v130, v131
	v_cvt_pk_bf16_f32 v132, v112, v113
	v_cvt_pk_bf16_f32 v133, v116, v117
	v_cvt_pk_bf16_f32 v134, v114, v115
	v_cvt_pk_bf16_f32 v135, v118, v130
	global_store_dwordx4 v[128:129], v[132:135], off offset:256 sc1
	v_cndmask_b32_e64 v128, 0, 1, s[46:47]
	v_cmp_ne_u32_e64 s[42:43], 1, v128
	s_cbranch_vccnz .LBB0_194
; __device__ __forceinline__ unsigned cvt_pk_bf16(float lo, float hi) { unsigned r; asm volatile("v_cvt_pk_bf16_f32 %0, %1, %2" : "=v"(r) : "v"(lo), "v"(hi)); return r; }
;     __device__ __forceinline__ void operator()(const f32x4 (&acc)[2][2][4][2], const Unit& u, int wr, int wc, int fr, int fq) const {
;     ...
;                         for (int e = 0; e < 4; ++e) { v0[e] = gelu_tanh(v0[e]); v1[e] = gelu_tanh(v1[e]); s += v0[e] + v1[e]; q += v0[e] * v0[e] + v1[e] * v1[e]; } }
;                     u32x4 w; w.x = cvt_pk_bf16(v0[0], v0[1]); w.y = cvt_pk_bf16(v0[2], v0[3]); w.z = cvt_pk_bf16(v1[0], v1[1]); w.w = cvt_pk_bf16(v1[2], v1[3]);
;                     *(u32x4*)(rowp + bj * HALF) = w; }
;                 if (ACT == 2) { if (u.pn >= 8) { s += __shfl_xor(s, 16); s += __shfl_xor(s, 32); q += __shfl_xor(q, 16); q += __shfl_xor(q, 32);
;                     if (fq == 0) *(f32x2*)(stats + ((size_t)row * 32 + (u.pn - 8) * 4 + wc) * 2) = (f32x2){s, q}; } }
	v_mul_f32_e32 v128, v122, v122
	v_mul_f32_e32 v129, v123, v123
	v_mul_f32_e32 v132, v126, v126
	v_mul_f32_e32 v133, v127, v127
	v_fma_f32 v128, v120, v120, v128
	v_fma_f32 v129, v121, v121, v129
	v_fma_f32 v132, v124, v124, v132
	v_fma_f32 v133, v125, v125, v133
	v_add_f32_e32 v128, v128, v129
	v_mul_f32_e32 v134, v114, v114
	v_mul_f32_e32 v135, v115, v115
	v_add_f32_e32 v128, v132, v128
	v_fma_f32 v134, v112, v112, v134
	v_fma_f32 v135, v113, v113, v135
	v_add_f32_e32 v128, v133, v128
	v_add_f32_e32 v128, v134, v128
	v_add_f32_e32 v129, v135, v128
	v_add_f32_e32 v128, v134, v128
	v_add_f32_e32 v120, v120, v122
	v_add_f32_e32 v121, v121, v123
	v_mov_b32_e32 v132, v116
	v_mov_b32_e32 v133, v118
	v_mul_f32_e32 v128, v116, v116
	v_add_f32_e32 v134, v116, v118
	v_add_f32_e32 v135, v117, v119
	v_mul_f32_e32 v118, v116, v118
	v_mul_f32_e32 v119, v117, v119
	v_add_f32_e32 v116, 0, v120
	v_add_f32_e32 v116, v121, v116
	v_add_f32_e32 v120, v124, v126
	v_add_f32_e32 v121, v125, v127
	v_add_f32_e32 v112, v112, v114
	v_add_f32_e32 v113, v113, v115
	v_add_f32_e32 v116, v120, v116
	v_add_f32_e32 v116, v121, v116
	v_fma_f32 v132, v132, v132, v128
	v_fma_f32 v133, v133, v133, v128
	v_add_f32_e32 v112, v112, v116
	v_mov_b32_e32 v135, v119
	v_mul_f32_e32 v119, v130, v130
	v_add_f32_e32 v118, v113, v112
	v_mov_b32_e32 v132, v117
	v_mov_b32_e32 v131, v129
	v_add_f32_e32 v112, v134, v118
	v_add_f32_e32 v113, v135, v119
	v_add_f32_e32 v114, v132, v130
	v_add_f32_e32 v115, v133, v131
	s_nop 0
	v_add_f32_e32 v112, v112, v114
	v_add_f32_e32 v113, v113, v115
	ds_bpermute_b32 v114, v205, v112
	ds_bpermute_b32 v115, v205, v113
	s_waitcnt lgkmcnt(0)
	v_add_f32_e32 v112, v112, v114
	v_add_f32_e32 v113, v113, v115
	ds_bpermute_b32 v114, v206, v112
	ds_bpermute_b32 v115, v206, v113
	s_and_saveexec_b64 s[44:45], s[38:39]
	s_cbranch_execz .LBB0_193
	v_lshlrev_b64 v[116:117], 8, v[194:195]
	s_waitcnt lgkmcnt(0)
	v_add_f32_e32 v112, v112, v114
	v_add_f32_e32 v113, v113, v115
	v_lshl_add_u64 v[114:115], s[6:7], 0, v[116:117]
	v_lshl_add_u64 v[114:115], s[36:37], 3, v[114:115]
	global_store_dwordx2 v[114:115], v[112:113], off

; __device__ __forceinline__ unsigned cvt_pk_bf16(float lo, float hi) { unsigned r; asm volatile("v_cvt_pk_bf16_f32 %0, %1, %2" : "=v"(r) : "v"(lo), "v"(hi)); return r; }
; __device__ __forceinline__ float gelu_tanh(float x) {
;     const float u = x * (0.7978845608f + 0.0356774081f * x * x);
;     const float e = __builtin_amdgcn_exp2f(u * 2.8853900818f);
;     return x - x * __builtin_amdgcn_rcpf(e + 1.0f);
; }
;     __device__ __forceinline__ void operator()(const f32x4 (&acc)[2][2][4][2], const Unit& u, int wr, int wc, int fr, int fq) const {
;     ...
;               for (int m = 0; m < 4; ++m) { float t = (pq[ai][m][0] + pq[ai][m][1]) + (pq[ai][m][2] + pq[ai][m][3]); t += __shfl_xor(t, 16); t += __shfl_xor(t, 32);
;                   rsv[ai][m] = rsqrtf(t * (1.f / DM) + EPS); } }
; #pragma unroll
;         for (int ai = 0; ai < 2; ++ai)
; #pragma unroll
;             for (int m = 0; m < 4; ++m) { const int row = row0 + ai * HALF + m * 16; bf16_t* rowp = O + (size_t)row * ldc + col0; float s = 0.f, q = 0.f;
;                 const float rstd = rsv[ai][m];
; #pragma unroll
;                 for (int bj = 0; bj < 2; ++bj) { f32x4 v0 = acc[ai][bj][m][0] * rstd + bv[bj][0], v1 = acc[ai][bj][m][1] * rstd + bv[bj][1];
;                     if (ACT == 1) {
; #pragma unroll
;                         for (int e = 0; e < 4; ++e) { const float a = fmaxf(v0[e], 0.f), b2 = fmaxf(v1[e], 0.f); v0[e] = a * a; v1[e] = b2 * b2; } }
;                     if (ACT == 2) {
; #pragma unroll
;                         for (int e = 0; e < 4; ++e) { v0[e] = gelu_tanh(v0[e]); v1[e] = gelu_tanh(v1[e]); s += v0[e] + v1[e]; q += v0[e] * v0[e] + v1[e] * v1[e]; } }
;                     u32x4 w; w.x = cvt_pk_bf16(v0[0], v0[1]); w.y = cvt_pk_bf16(v0[2], v0[3]); w.z = cvt_pk_bf16(v1[0], v1[1]); w.w = cvt_pk_bf16(v1[2], v1[3]);
;                     *(u32x4*)(rowp + bj * HALF) = w; }
.LBB0_194:
	v_add_f32_e32 v112, v160, v162
	v_add_f32_e32 v113, v161, v163
	s_mov_b32 s16, 0x3a800000
	v_fma_f32 v112, v112, s16, v214
	v_fma_f32 v113, v113, s16, v214
	s_waitcnt lgkmcnt(1)
	v_mul_f32_e32 v114, 0x4b800000, v113
	v_cmp_gt_f32_e32 vcc, s27, v113
	v_cmp_gt_f32_e64 s[44:45], s27, v112
	s_nop 0
	v_cndmask_b32_e32 v113, v113, v114, vcc
	v_rsq_f32_e32 v113, v113
	s_nop 0
	v_mul_f32_e32 v114, 0x45800000, v113
	v_cndmask_b32_e32 v120, v113, v114, vcc
	v_fma_f32 v116, v106, v120, v42
	v_fma_f32 v117, v107, v120, v43
	v_fma_f32 v106, v104, v120, v40
	v_fma_f32 v107, v105, v120, v41
	v_fma_f32 v108, v108, v120, v44
	v_fma_f32 v109, v109, v120, v45
	v_mul_f32_e32 v105, 0x3d122279, v106
	v_fmaak_f32 v105, v106, v105, 0x3f4c422a
	v_mul_f32_e32 v105, v106, v105
	v_mul_f32_e32 v105, 0x4038aa3b, v105
	v_exp_f32_e32 v105, v105
	v_mul_f32_e32 v104, 0x3d122279, v108
	v_fmaak_f32 v104, v108, v104, 0x3f4c422a
	v_mul_f32_e32 v104, v108, v104
	v_add_f32_e32 v105, 1.0, v105
	v_rcp_f32_e32 v118, v105
	v_mul_f32_e32 v105, 0x3d122279, v109
	v_fmaak_f32 v105, v109, v105, 0x3f4c422a
	v_mul_f32_e32 v105, v109, v105
	v_mul_f32_e32 v104, 0x4038aa3b, v104
	v_mul_f32_e32 v105, 0x4038aa3b, v105
	v_exp_f32_e32 v104, v104
	v_exp_f32_e32 v105, v105
	v_mul_f32_e32 v113, 0x3d122279, v107
	v_fmaak_f32 v113, v107, v113, 0x3f4c422a
	v_add_f32_e32 v104, 1.0, v104
	v_add_f32_e32 v105, 1.0, v105
	v_rcp_f32_e32 v104, v104
	v_rcp_f32_e32 v105, v105
	v_mul_f32_e32 v113, v107, v113
	v_mul_f32_e32 v113, 0x4038aa3b, v113
	v_exp_f32_e32 v113, v113
	v_fma_f32 v104, -v108, v104, v108
	v_fma_f32 v105, -v109, v105, v109
	v_mul_f32_e32 v109, 0x3d122279, v116
	v_fmaak_f32 v109, v116, v109, 0x3f4c422a
	v_mul_f32_e32 v109, v116, v109
	v_mul_f32_e32 v109, 0x4038aa3b, v109
	v_add_f32_e32 v113, 1.0, v113
	v_exp_f32_e32 v109, v109
	v_rcp_f32_e32 v119, v113
	v_fma_f32 v110, v110, v120, v46
	v_fma_f32 v111, v111, v120, v47
	v_mul_f32_e32 v113, 0x3d122279, v117
	v_add_f32_e32 v109, 1.0, v109
	v_fma_f32 v106, -v106, v118, v106
	v_fma_f32 v107, -v107, v119, v107
	v_mul_f32_e32 v108, 0x3d122279, v110
	v_rcp_f32_e32 v118, v109
	v_mul_f32_e32 v109, 0x3d122279, v111
	v_fmaak_f32 v108, v110, v108, 0x3f4c422a
	v_fmaak_f32 v109, v111, v109, 0x3f4c422a
	v_fmaak_f32 v113, v117, v113, 0x3f4c422a
	v_mul_f32_e32 v108, v110, v108
	v_mul_f32_e32 v109, v111, v109
	v_mul_f32_e32 v113, v117, v113
	v_mul_f32_e32 v108, 0x4038aa3b, v108
	v_mul_f32_e32 v109, 0x4038aa3b, v109
	v_mul_f32_e32 v113, 0x4038aa3b, v113
	v_exp_f32_e32 v108, v108
	v_exp_f32_e32 v109, v109
	v_exp_f32_e32 v113, v113
	s_waitcnt lgkmcnt(0)
	v_lshlrev_b64 v[114:115], 13, v[192:193]
	v_add_f32_e32 v108, 1.0, v108
	v_add_f32_e32 v109, 1.0, v109
	v_add_f32_e32 v113, 1.0, v113
	v_rcp_f32_e32 v108, v108
	v_rcp_f32_e32 v109, v109
	v_rcp_f32_e32 v119, v113
	v_lshl_add_u64 v[114:115], s[2:3], 0, v[114:115]
	v_lshl_add_u64 v[114:115], v[182:183], 1, v[114:115]
	v_fma_f32 v108, -v110, v108, v110
	v_fma_f32 v109, -v111, v109, v111
	v_fma_f32 v110, -v116, v118, v116
	v_fma_f32 v111, -v117, v119, v117
	v_cvt_pk_bf16_f32 v116, v104, v105
	v_cvt_pk_bf16_f32 v117, v108, v109
	v_cvt_pk_bf16_f32 v118, v106, v107
	v_fma_f32 v100, v100, v120, v36
	v_fma_f32 v101, v101, v120, v37
	v_cvt_pk_bf16_f32 v119, v110, v111
	global_store_dwordx4 v[114:115], v[116:119], off sc1
	v_fma_f32 v102, v102, v120, v38
	v_fma_f32 v103, v103, v120, v39
	s_and_b64 vcc, exec, s[42:43]
	v_fma_f32 v116, v98, v120, v34
	v_fma_f32 v117, v99, v120, v35
	v_fma_f32 v98, v96, v120, v32
	v_fma_f32 v99, v97, v120, v33
	v_mul_f32_e32 v96, 0x3d122279, v100
	v_mul_f32_e32 v97, 0x3d122279, v98
	v_fmaak_f32 v97, v98, v97, 0x3f4c422a
	v_mul_f32_e32 v97, v98, v97
	v_mul_f32_e32 v97, 0x4038aa3b, v97
	v_exp_f32_e32 v97, v97
	v_fmaak_f32 v96, v100, v96, 0x3f4c422a
	v_mul_f32_e32 v96, v100, v96
	v_mul_f32_e32 v96, 0x4038aa3b, v96
	v_add_f32_e32 v97, 1.0, v97
	v_rcp_f32_e32 v118, v97
	v_mul_f32_e32 v97, 0x3d122279, v101
	v_fmaak_f32 v97, v101, v97, 0x3f4c422a
	v_mul_f32_e32 v97, v101, v97
	v_mul_f32_e32 v97, 0x4038aa3b, v97
	v_exp_f32_e32 v96, v96
	v_exp_f32_e32 v97, v97
	v_mul_f32_e32 v113, 0x3d122279, v99
	v_fmaak_f32 v113, v99, v113, 0x3f4c422a
	v_add_f32_e32 v96, 1.0, v96
	v_add_f32_e32 v97, 1.0, v97
	v_rcp_f32_e32 v96, v96
	v_rcp_f32_e32 v97, v97
	v_mul_f32_e32 v113, v99, v113
	v_mul_f32_e32 v113, 0x4038aa3b, v113
	v_exp_f32_e32 v113, v113
	v_fma_f32 v96, -v100, v96, v100
	v_fma_f32 v97, -v101, v97, v101
	v_mul_f32_e32 v101, 0x3d122279, v116
	v_fmaak_f32 v101, v116, v101, 0x3f4c422a
	v_mul_f32_e32 v101, v116, v101
	v_mul_f32_e32 v101, 0x4038aa3b, v101
	v_add_f32_e32 v113, 1.0, v113
	v_exp_f32_e32 v101, v101
	v_rcp_f32_e32 v119, v113
	v_mul_f32_e32 v100, 0x3d122279, v102
	v_mul_f32_e32 v113, 0x3d122279, v117
	v_add_f32_e32 v101, 1.0, v101
	v_fma_f32 v98, -v98, v118, v98
	v_fma_f32 v99, -v99, v119, v99
	v_rcp_f32_e32 v118, v101
	v_mul_f32_e32 v101, 0x3d122279, v103
	v_fmaak_f32 v101, v103, v101, 0x3f4c422a
	v_fmaak_f32 v100, v102, v100, 0x3f4c422a
	v_mul_f32_e32 v101, v103, v101
	v_fmaak_f32 v113, v117, v113, 0x3f4c422a
	v_mul_f32_e32 v100, v102, v100
	v_mul_f32_e32 v101, 0x4038aa3b, v101
	v_mul_f32_e32 v113, v117, v113
	v_mul_f32_e32 v100, 0x4038aa3b, v100
	v_exp_f32_e32 v101, v101
	v_mul_f32_e32 v113, 0x4038aa3b, v113
	v_exp_f32_e32 v100, v100
	v_exp_f32_e32 v113, v113
	v_add_f32_e32 v101, 1.0, v101
	v_rcp_f32_e32 v101, v101
	v_add_f32_e32 v100, 1.0, v100
	v_add_f32_e32 v113, 1.0, v113
	v_rcp_f32_e32 v100, v100
	v_rcp_f32_e32 v113, v113
	v_mov_b32_e32 v120, v116
	v_mov_b32_e32 v121, v103
	v_mov_b32_e32 v119, v101
	v_fma_f32 v100, -v102, v100, v102
	v_fma_f32 v101, -v103, v101, v103
	v_fma_f32 v102, -v120, v118, v120
	v_fma_f32 v103, -v121, v119, v121
	v_fma_f32 v116, -v117, v113, v117
	v_cvt_pk_bf16_f32 v118, v96, v97
	v_cvt_pk_bf16_f32 v119, v100, v101
	v_cvt_pk_bf16_f32 v120, v98, v99
	v_cvt_pk_bf16_f32 v121, v102, v116
	global_store_dwordx4 v[114:115], v[118:121], off offset:256 sc1
	s_cbranch_vccnz .LBB0_198
; __device__ __forceinline__ unsigned cvt_pk_bf16(float lo, float hi) { unsigned r; asm volatile("v_cvt_pk_bf16_f32 %0, %1, %2" : "=v"(r) : "v"(lo), "v"(hi)); return r; }
;     __device__ __forceinline__ void operator()(const f32x4 (&acc)[2][2][4][2], const Unit& u, int wr, int wc, int fr, int fq) const {
;     ...
;                         for (int e = 0; e < 4; ++e) { v0[e] = gelu_tanh(v0[e]); v1[e] = gelu_tanh(v1[e]); s += v0[e] + v1[e]; q += v0[e] * v0[e] + v1[e] * v1[e]; } }
;                     u32x4 w; w.x = cvt_pk_bf16(v0[0], v0[1]); w.y = cvt_pk_bf16(v0[2], v0[3]); w.z = cvt_pk_bf16(v1[0], v1[1]); w.w = cvt_pk_bf16(v1[2], v1[3]);
;                     *(u32x4*)(rowp + bj * HALF) = w; }
;                 if (ACT == 2) { if (u.pn >= 8) { s += __shfl_xor(s, 16); s += __shfl_xor(s, 32); q += __shfl_xor(q, 16); q += __shfl_xor(q, 32);
;                     if (fq == 0) *(f32x2*)(stats + ((size_t)row * 32 + (u.pn - 8) * 4 + wc) * 2) = (f32x2){s, q}; } }
	v_mul_f32_e32 v114, v106, v106
	v_mul_f32_e32 v115, v107, v107
	v_mul_f32_e32 v118, v110, v110
	v_mul_f32_e32 v119, v111, v111
	v_fma_f32 v114, v104, v104, v114
	v_fma_f32 v115, v105, v105, v115
	v_fma_f32 v118, v108, v108, v118
	v_fma_f32 v119, v109, v109, v119
	v_add_f32_e32 v113, v114, v115
	v_mul_f32_e32 v120, v98, v98
	v_mul_f32_e32 v121, v99, v99
	v_add_f32_e32 v113, v118, v113
	v_fma_f32 v120, v96, v96, v120
	v_fma_f32 v121, v97, v97, v121
	v_add_f32_e32 v113, v119, v113
	v_add_f32_e32 v114, v120, v113
	v_add_f32_e32 v115, v121, v114
	v_add_f32_e32 v114, v120, v114
	v_add_f32_e32 v104, v104, v106
	v_add_f32_e32 v105, v105, v107
	v_mov_b32_e32 v118, v100
	v_mov_b32_e32 v119, v102
	v_mul_f32_e32 v114, v100, v100
	v_add_f32_e32 v120, v100, v102
	v_add_f32_e32 v121, v101, v103
	v_mul_f32_e32 v102, v100, v102
	v_mul_f32_e32 v103, v101, v103
	v_add_f32_e32 v100, 0, v104
	v_add_f32_e32 v100, v105, v100
	v_add_f32_e32 v104, v108, v110
	v_add_f32_e32 v105, v109, v111
	v_add_f32_e32 v96, v96, v98
	v_add_f32_e32 v97, v97, v99
	v_add_f32_e32 v100, v104, v100
	v_add_f32_e32 v100, v105, v100
	v_fma_f32 v118, v118, v118, v114
	v_fma_f32 v119, v119, v119, v114
	v_add_f32_e32 v96, v96, v100
	v_mov_b32_e32 v121, v103
	v_mul_f32_e32 v103, v116, v116
	v_add_f32_e32 v102, v97, v96
	v_mov_b32_e32 v118, v101
	v_mov_b32_e32 v117, v115
	v_add_f32_e32 v96, v120, v102
	v_add_f32_e32 v97, v121, v103
	v_add_f32_e32 v98, v118, v116
	v_add_f32_e32 v99, v119, v117
	s_nop 0
	v_add_f32_e32 v96, v96, v98
	v_add_f32_e32 v97, v97, v99
	ds_bpermute_b32 v98, v205, v96
	ds_bpermute_b32 v99, v205, v97
	s_waitcnt lgkmcnt(0)
	v_add_f32_e32 v96, v96, v98
	v_add_f32_e32 v97, v97, v99
	ds_bpermute_b32 v98, v206, v96
	ds_bpermute_b32 v99, v206, v97
	s_and_saveexec_b64 s[46:47], s[38:39]
	s_cbranch_execz .LBB0_197
	v_lshlrev_b64 v[100:101], 8, v[192:193]
	s_waitcnt lgkmcnt(0)
	v_add_f32_e32 v96, v96, v98
	v_add_f32_e32 v97, v97, v99
	v_lshl_add_u64 v[98:99], s[6:7], 0, v[100:101]
	v_lshl_add_u64 v[98:99], s[36:37], 3, v[98:99]
	global_store_dwordx2 v[98:99], v[96:97], off

; __device__ __forceinline__ unsigned cvt_pk_bf16(float lo, float hi) { unsigned r; asm volatile("v_cvt_pk_bf16_f32 %0, %1, %2" : "=v"(r) : "v"(lo), "v"(hi)); return r; }
; __device__ __forceinline__ float gelu_tanh(float x) {
;     const float u = x * (0.7978845608f + 0.0356774081f * x * x);
;     const float e = __builtin_amdgcn_exp2f(u * 2.8853900818f);
;     return x - x * __builtin_amdgcn_rcpf(e + 1.0f);
; }
;     __device__ __forceinline__ void operator()(const f32x4 (&acc)[2][2][4][2], const Unit& u, int wr, int wc, int fr, int fq) const {
;     ...
;                 for (int bj = 0; bj < 2; ++bj) { f32x4 v0 = acc[ai][bj][m][0] * rstd + bv[bj][0], v1 = acc[ai][bj][m][1] * rstd + bv[bj][1];
;                     if (ACT == 1) {
; #pragma unroll
;                         for (int e = 0; e < 4; ++e) { const float a = fmaxf(v0[e], 0.f), b2 = fmaxf(v1[e], 0.f); v0[e] = a * a; v1[e] = b2 * b2; } }
;                     if (ACT == 2) {
; #pragma unroll
;                         for (int e = 0; e < 4; ++e) { v0[e] = gelu_tanh(v0[e]); v1[e] = gelu_tanh(v1[e]); s += v0[e] + v1[e]; q += v0[e] * v0[e] + v1[e] * v1[e]; } }
;                     u32x4 w; w.x = cvt_pk_bf16(v0[0], v0[1]); w.y = cvt_pk_bf16(v0[2], v0[3]); w.z = cvt_pk_bf16(v1[0], v1[1]); w.w = cvt_pk_bf16(v1[2], v1[3]);
;                     *(u32x4*)(rowp + bj * HALF) = w; }
.LBB0_198:
	v_mul_f32_e32 v96, 0x4b800000, v112
	v_cndmask_b32_e64 v96, v112, v96, s[44:45]
	v_rsq_f32_e32 v96, v96
	s_and_b64 vcc, exec, s[42:43]
	v_mul_f32_e32 v97, 0x45800000, v96
	v_cndmask_b32_e64 v102, v96, v97, s[44:45]
	s_waitcnt lgkmcnt(0)
	v_fma_f32 v98, v90, v102, v42
	v_fma_f32 v99, v91, v102, v43
	v_fma_f32 v90, v88, v102, v40
	v_fma_f32 v91, v89, v102, v41
	v_fma_f32 v92, v92, v102, v44
	v_fma_f32 v93, v93, v102, v45
	v_mul_f32_e32 v89, 0x3d122279, v90
	v_fmaak_f32 v89, v90, v89, 0x3f4c422a
	v_mul_f32_e32 v89, v90, v89
	v_mul_f32_e32 v89, 0x4038aa3b, v89
	v_exp_f32_e32 v89, v89
	v_mul_f32_e32 v88, 0x3d122279, v92
	v_fmaak_f32 v88, v92, v88, 0x3f4c422a
	v_mul_f32_e32 v88, v92, v88
	v_add_f32_e32 v89, 1.0, v89
	v_rcp_f32_e32 v100, v89
	v_mul_f32_e32 v89, 0x3d122279, v93
	v_fmaak_f32 v89, v93, v89, 0x3f4c422a
	v_mul_f32_e32 v89, v93, v89
	v_mul_f32_e32 v88, 0x4038aa3b, v88
	v_mul_f32_e32 v89, 0x4038aa3b, v89
	v_exp_f32_e32 v88, v88
	v_exp_f32_e32 v89, v89
	v_mul_f32_e32 v101, 0x3d122279, v91
	v_fmaak_f32 v101, v91, v101, 0x3f4c422a
	v_add_f32_e32 v88, 1.0, v88
	v_add_f32_e32 v89, 1.0, v89
	v_rcp_f32_e32 v88, v88
	v_rcp_f32_e32 v89, v89
	v_mul_f32_e32 v101, v91, v101
	v_mul_f32_e32 v101, 0x4038aa3b, v101
	v_exp_f32_e32 v101, v101
	v_fma_f32 v88, -v92, v88, v92
	v_fma_f32 v89, -v93, v89, v93
	v_mul_f32_e32 v93, 0x3d122279, v98
	v_fmaak_f32 v93, v98, v93, 0x3f4c422a
	v_mul_f32_e32 v93, v98, v93
	v_mul_f32_e32 v93, 0x4038aa3b, v93
	v_add_f32_e32 v101, 1.0, v101
	v_exp_f32_e32 v93, v93
	v_rcp_f32_e32 v101, v101
	v_fma_f32 v94, v94, v102, v46
	v_fma_f32 v95, v95, v102, v47
	v_lshlrev_b64 v[96:97], 13, v[190:191]
	v_add_f32_e32 v93, 1.0, v93
	v_fma_f32 v90, -v90, v100, v90
	v_fma_f32 v91, -v91, v101, v91
	v_mul_f32_e32 v92, 0x3d122279, v94
	v_rcp_f32_e32 v100, v93
	v_mul_f32_e32 v93, 0x3d122279, v95
	v_mul_f32_e32 v101, 0x3d122279, v99
	v_fmaak_f32 v92, v94, v92, 0x3f4c422a
	v_fmaak_f32 v93, v95, v93, 0x3f4c422a
	v_fmaak_f32 v101, v99, v101, 0x3f4c422a
	v_mul_f32_e32 v92, v94, v92
	v_mul_f32_e32 v93, v95, v93
	v_mul_f32_e32 v101, v99, v101
	v_mul_f32_e32 v92, 0x4038aa3b, v92
	v_mul_f32_e32 v93, 0x4038aa3b, v93
	v_mul_f32_e32 v101, 0x4038aa3b, v101
	v_exp_f32_e32 v92, v92
	v_exp_f32_e32 v93, v93
	v_exp_f32_e32 v101, v101
	v_lshl_add_u64 v[96:97], s[2:3], 0, v[96:97]
	v_add_f32_e32 v92, 1.0, v92
	v_add_f32_e32 v93, 1.0, v93
	v_add_f32_e32 v101, 1.0, v101
	v_rcp_f32_e32 v92, v92
	v_rcp_f32_e32 v93, v93
	v_rcp_f32_e32 v101, v101
	v_lshl_add_u64 v[96:97], v[182:183], 1, v[96:97]
	v_fma_f32 v84, v84, v102, v36
	v_fma_f32 v85, v85, v102, v37
	v_fma_f32 v92, -v94, v92, v94
	v_fma_f32 v93, -v95, v93, v95
	v_fma_f32 v94, -v98, v100, v98
	v_fma_f32 v95, -v99, v101, v99
	v_cvt_pk_bf16_f32 v98, v88, v89
	v_cvt_pk_bf16_f32 v99, v92, v93
	v_cvt_pk_bf16_f32 v100, v90, v91
	v_fma_f32 v86, v86, v102, v38
	v_fma_f32 v87, v87, v102, v39
	v_cvt_pk_bf16_f32 v101, v94, v95
	global_store_dwordx4 v[96:97], v[98:101], off sc1
	s_nop 1
	v_fma_f32 v98, v82, v102, v34
	v_fma_f32 v99, v83, v102, v35
	v_fma_f32 v82, v80, v102, v32
	v_fma_f32 v83, v81, v102, v33
	v_mul_f32_e32 v80, 0x3d122279, v84
	v_mul_f32_e32 v81, 0x3d122279, v82
	v_fmaak_f32 v81, v82, v81, 0x3f4c422a
	v_mul_f32_e32 v81, v82, v81
	v_mul_f32_e32 v81, 0x4038aa3b, v81
	v_exp_f32_e32 v81, v81
	v_fmaak_f32 v80, v84, v80, 0x3f4c422a
	v_mul_f32_e32 v80, v84, v80
	v_mul_f32_e32 v80, 0x4038aa3b, v80
	v_add_f32_e32 v81, 1.0, v81
	v_rcp_f32_e32 v100, v81
	v_mul_f32_e32 v81, 0x3d122279, v85
	v_fmaak_f32 v81, v85, v81, 0x3f4c422a
	v_mul_f32_e32 v81, v85, v81
	v_mul_f32_e32 v81, 0x4038aa3b, v81
	v_exp_f32_e32 v80, v80
	v_exp_f32_e32 v81, v81
	v_mul_f32_e32 v101, 0x3d122279, v83
	v_fmaak_f32 v101, v83, v101, 0x3f4c422a
	v_add_f32_e32 v80, 1.0, v80
	v_add_f32_e32 v81, 1.0, v81
	v_rcp_f32_e32 v80, v80
	v_rcp_f32_e32 v81, v81
	v_mul_f32_e32 v101, v83, v101
	v_mul_f32_e32 v101, 0x4038aa3b, v101
	v_exp_f32_e32 v101, v101
	v_fma_f32 v80, -v84, v80, v84
	v_fma_f32 v81, -v85, v81, v85
	v_mul_f32_e32 v85, 0x3d122279, v98
	v_fmaak_f32 v85, v98, v85, 0x3f4c422a
	v_mul_f32_e32 v85, v98, v85
	v_mul_f32_e32 v85, 0x4038aa3b, v85
	v_add_f32_e32 v101, 1.0, v101
	v_exp_f32_e32 v85, v85
	v_rcp_f32_e32 v101, v101
	v_mul_f32_e32 v84, 0x3d122279, v86
	v_mov_b32_e32 v102, v98
	v_add_f32_e32 v85, 1.0, v85
	v_fma_f32 v82, -v82, v100, v82
	v_fma_f32 v83, -v83, v101, v83
	v_rcp_f32_e32 v100, v85
	v_mul_f32_e32 v85, 0x3d122279, v87
	v_fmaak_f32 v85, v87, v85, 0x3f4c422a
	v_mul_f32_e32 v98, 0x3d122279, v99
	v_fmaak_f32 v84, v86, v84, 0x3f4c422a
	v_mul_f32_e32 v85, v87, v85
	v_fmaak_f32 v98, v99, v98, 0x3f4c422a
	v_mul_f32_e32 v84, v86, v84
	v_mul_f32_e32 v85, 0x4038aa3b, v85
	v_mul_f32_e32 v98, v99, v98
	v_mul_f32_e32 v84, 0x4038aa3b, v84
	v_exp_f32_e32 v85, v85
	v_mul_f32_e32 v98, 0x4038aa3b, v98
	v_exp_f32_e32 v84, v84
	v_exp_f32_e32 v98, v98
	v_add_f32_e32 v85, 1.0, v85
	v_rcp_f32_e32 v85, v85
	v_add_f32_e32 v84, 1.0, v84
	v_add_f32_e32 v98, 1.0, v98
	v_rcp_f32_e32 v84, v84
	v_rcp_f32_e32 v98, v98
	v_mov_b32_e32 v103, v87
	v_mov_b32_e32 v101, v85
	v_fma_f32 v84, -v86, v84, v86
	v_fma_f32 v85, -v87, v85, v87
	v_fma_f32 v86, -v102, v100, v102
	v_fma_f32 v87, -v103, v101, v103
	v_fma_f32 v98, -v99, v98, v99
	v_cvt_pk_bf16_f32 v100, v80, v81
	v_cvt_pk_bf16_f32 v101, v84, v85
	v_cvt_pk_bf16_f32 v102, v82, v83
	v_cvt_pk_bf16_f32 v103, v86, v98
	global_store_dwordx4 v[96:97], v[100:103], off offset:256 sc1
	s_cbranch_vccnz .LBB0_202
; __device__ __forceinline__ unsigned cvt_pk_bf16(float lo, float hi) { unsigned r; asm volatile("v_cvt_pk_bf16_f32 %0, %1, %2" : "=v"(r) : "v"(lo), "v"(hi)); return r; }
;     __device__ __forceinline__ void operator()(const f32x4 (&acc)[2][2][4][2], const Unit& u, int wr, int wc, int fr, int fq) const {
;     ...
;                         for (int e = 0; e < 4; ++e) { v0[e] = gelu_tanh(v0[e]); v1[e] = gelu_tanh(v1[e]); s += v0[e] + v1[e]; q += v0[e] * v0[e] + v1[e] * v1[e]; } }
;                     u32x4 w; w.x = cvt_pk_bf16(v0[0], v0[1]); w.y = cvt_pk_bf16(v0[2], v0[3]); w.z = cvt_pk_bf16(v1[0], v1[1]); w.w = cvt_pk_bf16(v1[2], v1[3]);
;                     *(u32x4*)(rowp + bj * HALF) = w; }
;                 if (ACT == 2) { if (u.pn >= 8) { s += __shfl_xor(s, 16); s += __shfl_xor(s, 32); q += __shfl_xor(q, 16); q += __shfl_xor(q, 32);
;                     if (fq == 0) *(f32x2*)(stats + ((size_t)row * 32 + (u.pn - 8) * 4 + wc) * 2) = (f32x2){s, q}; } }
	v_mul_f32_e32 v96, v90, v90
	v_mul_f32_e32 v97, v91, v91
	v_mul_f32_e32 v100, v94, v94
	v_mul_f32_e32 v101, v95, v95
	v_fma_f32 v96, v88, v88, v96
	v_fma_f32 v97, v89, v89, v97
	v_fma_f32 v100, v92, v92, v100
	v_fma_f32 v101, v93, v93, v101
	v_add_f32_e32 v96, v96, v97
	v_mul_f32_e32 v102, v82, v82
	v_mul_f32_e32 v103, v83, v83
	v_add_f32_e32 v96, v100, v96
	v_fma_f32 v102, v80, v80, v102
	v_fma_f32 v103, v81, v81, v103
	v_add_f32_e32 v96, v101, v96
	v_add_f32_e32 v96, v102, v96
	v_add_f32_e32 v97, v103, v96
	v_add_f32_e32 v96, v102, v96
	v_add_f32_e32 v88, v88, v90
	v_add_f32_e32 v89, v89, v91
	v_mov_b32_e32 v100, v84
	v_mov_b32_e32 v101, v86
	v_mul_f32_e32 v96, v84, v84
	v_add_f32_e32 v102, v84, v86
	v_add_f32_e32 v103, v85, v87
	v_mul_f32_e32 v86, v84, v86
	v_mul_f32_e32 v87, v85, v87
	v_add_f32_e32 v84, 0, v88
	v_add_f32_e32 v84, v89, v84
	v_add_f32_e32 v88, v92, v94
	v_add_f32_e32 v89, v93, v95
	v_add_f32_e32 v80, v80, v82
	v_add_f32_e32 v81, v81, v83
	v_add_f32_e32 v84, v88, v84
	v_add_f32_e32 v84, v89, v84
	v_fma_f32 v100, v100, v100, v96
	v_fma_f32 v101, v101, v101, v96
	v_add_f32_e32 v80, v80, v84
	v_mov_b32_e32 v103, v87
	v_mul_f32_e32 v87, v98, v98
	v_add_f32_e32 v86, v81, v80
	v_mov_b32_e32 v100, v85
	v_mov_b32_e32 v99, v97
	v_add_f32_e32 v80, v102, v86
	v_add_f32_e32 v81, v103, v87
	v_add_f32_e32 v82, v100, v98
	v_add_f32_e32 v83, v101, v99
	s_nop 0
	v_add_f32_e32 v80, v80, v82
	v_add_f32_e32 v81, v81, v83
	ds_bpermute_b32 v82, v205, v80
	ds_bpermute_b32 v83, v205, v81
	s_waitcnt lgkmcnt(0)
	v_add_f32_e32 v80, v80, v82
	v_add_f32_e32 v81, v81, v83
	ds_bpermute_b32 v82, v206, v80
	ds_bpermute_b32 v83, v206, v81
	s_and_saveexec_b64 s[44:45], s[38:39]
	s_cbranch_execz .LBB0_201
	v_lshlrev_b64 v[84:85], 8, v[190:191]
	s_waitcnt lgkmcnt(0)
	v_add_f32_e32 v80, v80, v82
	v_add_f32_e32 v81, v81, v83
	v_lshl_add_u64 v[82:83], s[6:7], 0, v[84:85]
	v_lshl_add_u64 v[82:83], s[36:37], 3, v[82:83]
	global_store_dwordx2 v[82:83], v[80:81], off

; __device__ __forceinline__ unsigned cvt_pk_bf16(float lo, float hi) { unsigned r; asm volatile("v_cvt_pk_bf16_f32 %0, %1, %2" : "=v"(r) : "v"(lo), "v"(hi)); return r; }
; __device__ __forceinline__ float gelu_tanh(float x) {
;     const float u = x * (0.7978845608f + 0.0356774081f * x * x);
;     const float e = __builtin_amdgcn_exp2f(u * 2.8853900818f);
;     return x - x * __builtin_amdgcn_rcpf(e + 1.0f);
; }
;     __device__ __forceinline__ void operator()(const f32x4 (&acc)[2][2][4][2], const Unit& u, int wr, int wc, int fr, int fq) const {
;     ...
;               for (int m = 0; m < 4; ++m) { float t = (pq[ai][m][0] + pq[ai][m][1]) + (pq[ai][m][2] + pq[ai][m][3]); t += __shfl_xor(t, 16); t += __shfl_xor(t, 32);
;                   rsv[ai][m] = rsqrtf(t * (1.f / DM) + EPS); } }
; #pragma unroll
;         for (int ai = 0; ai < 2; ++ai)
; #pragma unroll
;             for (int m = 0; m < 4; ++m) { const int row = row0 + ai * HALF + m * 16; bf16_t* rowp = O + (size_t)row * ldc + col0; float s = 0.f, q = 0.f;
;                 const float rstd = rsv[ai][m];
; #pragma unroll
;                 for (int bj = 0; bj < 2; ++bj) { f32x4 v0 = acc[ai][bj][m][0] * rstd + bv[bj][0], v1 = acc[ai][bj][m][1] * rstd + bv[bj][1];
;                     if (ACT == 1) {
; #pragma unroll
;                         for (int e = 0; e < 4; ++e) { const float a = fmaxf(v0[e], 0.f), b2 = fmaxf(v1[e], 0.f); v0[e] = a * a; v1[e] = b2 * b2; } }
;                     if (ACT == 2) {
; #pragma unroll
;                         for (int e = 0; e < 4; ++e) { v0[e] = gelu_tanh(v0[e]); v1[e] = gelu_tanh(v1[e]); s += v0[e] + v1[e]; q += v0[e] * v0[e] + v1[e] * v1[e]; } }
;                     u32x4 w; w.x = cvt_pk_bf16(v0[0], v0[1]); w.y = cvt_pk_bf16(v0[2], v0[3]); w.z = cvt_pk_bf16(v1[0], v1[1]); w.w = cvt_pk_bf16(v1[2], v1[3]);
;                     *(u32x4*)(rowp + bj * HALF) = w; }
.LBB0_202:
	v_add_f32_e32 v80, v152, v154
	v_add_f32_e32 v81, v153, v155
	s_nop 0
	v_fma_f32 v80, v80, s16, v214
	v_fma_f32 v81, v81, s16, v214
	s_waitcnt lgkmcnt(1)
	v_mul_f32_e32 v82, 0x4b800000, v81
	v_cmp_gt_f32_e32 vcc, s27, v81
	v_cmp_gt_f32_e64 s[44:45], s27, v80
	s_nop 0
	v_cndmask_b32_e32 v81, v81, v82, vcc
	v_rsq_f32_e32 v81, v81
	s_nop 0
	v_mul_f32_e32 v82, 0x45800000, v81
	v_cndmask_b32_e32 v88, v81, v82, vcc
	v_fma_f32 v84, v74, v88, v42
	v_fma_f32 v85, v75, v88, v43
	v_fma_f32 v74, v72, v88, v40
	v_fma_f32 v75, v73, v88, v41
	v_fma_f32 v76, v76, v88, v44
	v_fma_f32 v77, v77, v88, v45
	v_mul_f32_e32 v73, 0x3d122279, v74
	v_fmaak_f32 v73, v74, v73, 0x3f4c422a
	v_mul_f32_e32 v73, v74, v73
	v_mul_f32_e32 v73, 0x4038aa3b, v73
	v_exp_f32_e32 v73, v73
	v_mul_f32_e32 v72, 0x3d122279, v76
	v_fmaak_f32 v72, v76, v72, 0x3f4c422a
	v_mul_f32_e32 v72, v76, v72
	v_add_f32_e32 v73, 1.0, v73
	v_rcp_f32_e32 v86, v73
	v_mul_f32_e32 v73, 0x3d122279, v77
	v_fmaak_f32 v73, v77, v73, 0x3f4c422a
	v_mul_f32_e32 v73, v77, v73
	v_mul_f32_e32 v72, 0x4038aa3b, v72
	v_mul_f32_e32 v73, 0x4038aa3b, v73
	v_exp_f32_e32 v72, v72
	v_exp_f32_e32 v73, v73
	v_mul_f32_e32 v81, 0x3d122279, v75
	v_fmaak_f32 v81, v75, v81, 0x3f4c422a
	v_add_f32_e32 v72, 1.0, v72
	v_add_f32_e32 v73, 1.0, v73
	v_rcp_f32_e32 v72, v72
	v_rcp_f32_e32 v73, v73
	v_mul_f32_e32 v81, v75, v81
	v_mul_f32_e32 v81, 0x4038aa3b, v81
	v_exp_f32_e32 v81, v81
	v_fma_f32 v72, -v76, v72, v76
	v_fma_f32 v73, -v77, v73, v77
	v_mul_f32_e32 v77, 0x3d122279, v84
	v_fmaak_f32 v77, v84, v77, 0x3f4c422a
	v_mul_f32_e32 v77, v84, v77
	v_mul_f32_e32 v77, 0x4038aa3b, v77
	v_add_f32_e32 v81, 1.0, v81
	v_exp_f32_e32 v77, v77
	v_rcp_f32_e32 v87, v81
	v_fma_f32 v78, v78, v88, v46
	v_fma_f32 v79, v79, v88, v47
	v_mul_f32_e32 v81, 0x3d122279, v85
	v_add_f32_e32 v77, 1.0, v77
	v_fma_f32 v74, -v74, v86, v74
	v_fma_f32 v75, -v75, v87, v75
	v_mul_f32_e32 v76, 0x3d122279, v78
	v_rcp_f32_e32 v86, v77
	v_mul_f32_e32 v77, 0x3d122279, v79
	v_fmaak_f32 v76, v78, v76, 0x3f4c422a
	v_fmaak_f32 v77, v79, v77, 0x3f4c422a
	v_fmaak_f32 v81, v85, v81, 0x3f4c422a
	v_mul_f32_e32 v76, v78, v76
	v_mul_f32_e32 v77, v79, v77
	v_mul_f32_e32 v81, v85, v81
	v_mul_f32_e32 v76, 0x4038aa3b, v76
	v_mul_f32_e32 v77, 0x4038aa3b, v77
	v_mul_f32_e32 v81, 0x4038aa3b, v81
	v_exp_f32_e32 v76, v76
	v_exp_f32_e32 v77, v77
	v_exp_f32_e32 v81, v81
	s_waitcnt lgkmcnt(0)
	v_lshlrev_b64 v[82:83], 13, v[188:189]
	v_add_f32_e32 v76, 1.0, v76
	v_add_f32_e32 v77, 1.0, v77
	v_add_f32_e32 v81, 1.0, v81
	v_rcp_f32_e32 v76, v76
	v_rcp_f32_e32 v77, v77
	v_rcp_f32_e32 v87, v81
	v_lshl_add_u64 v[82:83], s[2:3], 0, v[82:83]
	v_lshl_add_u64 v[82:83], v[182:183], 1, v[82:83]
	v_fma_f32 v76, -v78, v76, v78
	v_fma_f32 v77, -v79, v77, v79
	v_fma_f32 v78, -v84, v86, v84
	v_fma_f32 v79, -v85, v87, v85
	v_cvt_pk_bf16_f32 v84, v72, v73
	v_cvt_pk_bf16_f32 v85, v76, v77
	v_cvt_pk_bf16_f32 v86, v74, v75
	v_fma_f32 v68, v68, v88, v36
	v_fma_f32 v69, v69, v88, v37
	v_cvt_pk_bf16_f32 v87, v78, v79
	global_store_dwordx4 v[82:83], v[84:87], off sc1
	v_fma_f32 v70, v70, v88, v38
	v_fma_f32 v71, v71, v88, v39
	s_and_b64 vcc, exec, s[42:43]
	v_fma_f32 v84, v66, v88, v34
	v_fma_f32 v85, v67, v88, v35
	v_fma_f32 v66, v64, v88, v32
	v_fma_f32 v67, v65, v88, v33
	v_mul_f32_e32 v64, 0x3d122279, v68
	v_mul_f32_e32 v65, 0x3d122279, v66
	v_fmaak_f32 v65, v66, v65, 0x3f4c422a
	v_mul_f32_e32 v65, v66, v65
	v_mul_f32_e32 v65, 0x4038aa3b, v65
	v_exp_f32_e32 v65, v65
	v_fmaak_f32 v64, v68, v64, 0x3f4c422a
	v_mul_f32_e32 v64, v68, v64
	v_mul_f32_e32 v64, 0x4038aa3b, v64
	v_add_f32_e32 v65, 1.0, v65
	v_rcp_f32_e32 v86, v65
	v_mul_f32_e32 v65, 0x3d122279, v69
	v_fmaak_f32 v65, v69, v65, 0x3f4c422a
	v_mul_f32_e32 v65, v69, v65
	v_mul_f32_e32 v65, 0x4038aa3b, v65
	v_exp_f32_e32 v64, v64
	v_exp_f32_e32 v65, v65
	v_mul_f32_e32 v81, 0x3d122279, v67
	v_fmaak_f32 v81, v67, v81, 0x3f4c422a
	v_add_f32_e32 v64, 1.0, v64
	v_add_f32_e32 v65, 1.0, v65
	v_rcp_f32_e32 v64, v64
	v_rcp_f32_e32 v65, v65
	v_mul_f32_e32 v81, v67, v81
	v_mul_f32_e32 v81, 0x4038aa3b, v81
	v_exp_f32_e32 v81, v81
	v_fma_f32 v64, -v68, v64, v68
	v_fma_f32 v65, -v69, v65, v69
	v_mul_f32_e32 v69, 0x3d122279, v84
	v_fmaak_f32 v69, v84, v69, 0x3f4c422a
	v_mul_f32_e32 v69, v84, v69
	v_mul_f32_e32 v69, 0x4038aa3b, v69
	v_add_f32_e32 v81, 1.0, v81
	v_exp_f32_e32 v69, v69
	v_rcp_f32_e32 v87, v81
	v_mul_f32_e32 v68, 0x3d122279, v70
	v_mul_f32_e32 v81, 0x3d122279, v85
	v_add_f32_e32 v69, 1.0, v69
	v_fma_f32 v66, -v66, v86, v66
	v_fma_f32 v67, -v67, v87, v67
	v_rcp_f32_e32 v86, v69
	v_mul_f32_e32 v69, 0x3d122279, v71
	v_fmaak_f32 v69, v71, v69, 0x3f4c422a
	v_fmaak_f32 v68, v70, v68, 0x3f4c422a
	v_mul_f32_e32 v69, v71, v69
	v_fmaak_f32 v81, v85, v81, 0x3f4c422a
	v_mul_f32_e32 v68, v70, v68
	v_mul_f32_e32 v69, 0x4038aa3b, v69
	v_mul_f32_e32 v81, v85, v81
	v_mul_f32_e32 v68, 0x4038aa3b, v68
	v_exp_f32_e32 v69, v69
	v_mul_f32_e32 v81, 0x4038aa3b, v81
	v_exp_f32_e32 v68, v68
	v_exp_f32_e32 v81, v81
	v_add_f32_e32 v69, 1.0, v69
	v_rcp_f32_e32 v69, v69
	v_add_f32_e32 v68, 1.0, v68
	v_add_f32_e32 v81, 1.0, v81
	v_rcp_f32_e32 v68, v68
	v_rcp_f32_e32 v81, v81
	v_mov_b32_e32 v88, v84
	v_mov_b32_e32 v89, v71
	v_mov_b32_e32 v87, v69
	v_fma_f32 v68, -v70, v68, v70
	v_fma_f32 v69, -v71, v69, v71
	v_fma_f32 v70, -v88, v86, v88
	v_fma_f32 v71, -v89, v87, v89
	v_fma_f32 v84, -v85, v81, v85
	v_cvt_pk_bf16_f32 v86, v64, v65
	v_cvt_pk_bf16_f32 v87, v68, v69
	v_cvt_pk_bf16_f32 v88, v66, v67
	v_cvt_pk_bf16_f32 v89, v70, v84
	global_store_dwordx4 v[82:83], v[86:89], off offset:256 sc1
	s_cbranch_vccnz .LBB0_206
; __device__ __forceinline__ unsigned cvt_pk_bf16(float lo, float hi) { unsigned r; asm volatile("v_cvt_pk_bf16_f32 %0, %1, %2" : "=v"(r) : "v"(lo), "v"(hi)); return r; }
;     __device__ __forceinline__ void operator()(const f32x4 (&acc)[2][2][4][2], const Unit& u, int wr, int wc, int fr, int fq) const {
;     ...
;                         for (int e = 0; e < 4; ++e) { v0[e] = gelu_tanh(v0[e]); v1[e] = gelu_tanh(v1[e]); s += v0[e] + v1[e]; q += v0[e] * v0[e] + v1[e] * v1[e]; } }
;                     u32x4 w; w.x = cvt_pk_bf16(v0[0], v0[1]); w.y = cvt_pk_bf16(v0[2], v0[3]); w.z = cvt_pk_bf16(v1[0], v1[1]); w.w = cvt_pk_bf16(v1[2], v1[3]);
;                     *(u32x4*)(rowp + bj * HALF) = w; }
;                 if (ACT == 2) { if (u.pn >= 8) { s += __shfl_xor(s, 16); s += __shfl_xor(s, 32); q += __shfl_xor(q, 16); q += __shfl_xor(q, 32);
;                     if (fq == 0) *(f32x2*)(stats + ((size_t)row * 32 + (u.pn - 8) * 4 + wc) * 2) = (f32x2){s, q}; } }
	v_mul_f32_e32 v82, v74, v74
	v_mul_f32_e32 v83, v75, v75
	v_mul_f32_e32 v86, v78, v78
	v_mul_f32_e32 v87, v79, v79
	v_fma_f32 v82, v72, v72, v82
	v_fma_f32 v83, v73, v73, v83
	v_fma_f32 v86, v76, v76, v86
	v_fma_f32 v87, v77, v77, v87
	v_add_f32_e32 v81, v82, v83
	v_mul_f32_e32 v88, v66, v66
	v_mul_f32_e32 v89, v67, v67
	v_add_f32_e32 v81, v86, v81
	v_fma_f32 v88, v64, v64, v88
	v_fma_f32 v89, v65, v65, v89
	v_add_f32_e32 v81, v87, v81
	v_add_f32_e32 v82, v88, v81
	v_add_f32_e32 v83, v89, v82
	v_add_f32_e32 v82, v88, v82
	v_add_f32_e32 v72, v72, v74
	v_add_f32_e32 v73, v73, v75
	v_mov_b32_e32 v86, v68
	v_mov_b32_e32 v87, v70
	v_mul_f32_e32 v82, v68, v68
	v_add_f32_e32 v88, v68, v70
	v_add_f32_e32 v89, v69, v71
	v_mul_f32_e32 v70, v68, v70
	v_mul_f32_e32 v71, v69, v71
	v_add_f32_e32 v68, 0, v72
	v_add_f32_e32 v68, v73, v68
	v_add_f32_e32 v72, v76, v78
	v_add_f32_e32 v73, v77, v79
	v_add_f32_e32 v64, v64, v66
	v_add_f32_e32 v65, v65, v67
	v_add_f32_e32 v68, v72, v68
	v_add_f32_e32 v68, v73, v68
	v_fma_f32 v86, v86, v86, v82
	v_fma_f32 v87, v87, v87, v82
	v_add_f32_e32 v64, v64, v68
	v_mov_b32_e32 v89, v71
	v_mul_f32_e32 v71, v84, v84
	v_add_f32_e32 v70, v65, v64
	v_mov_b32_e32 v86, v69
	v_mov_b32_e32 v85, v83
	v_add_f32_e32 v64, v88, v70
	v_add_f32_e32 v65, v89, v71
	v_add_f32_e32 v66, v86, v84
	v_add_f32_e32 v67, v87, v85
	s_nop 0
	v_add_f32_e32 v64, v64, v66
	v_add_f32_e32 v65, v65, v67
	ds_bpermute_b32 v66, v205, v64
	ds_bpermute_b32 v67, v205, v65
	s_waitcnt lgkmcnt(0)
	v_add_f32_e32 v64, v64, v66
	v_add_f32_e32 v65, v65, v67
	ds_bpermute_b32 v66, v206, v64
	ds_bpermute_b32 v67, v206, v65
	s_and_saveexec_b64 s[46:47], s[38:39]
	s_cbranch_execz .LBB0_205
	v_lshlrev_b64 v[68:69], 8, v[188:189]
	s_waitcnt lgkmcnt(0)
	v_add_f32_e32 v64, v64, v66
	v_add_f32_e32 v65, v65, v67
	v_lshl_add_u64 v[66:67], s[6:7], 0, v[68:69]
	v_lshl_add_u64 v[66:67], s[36:37], 3, v[66:67]
	global_store_dwordx2 v[66:67], v[64:65], off

; __device__ __forceinline__ unsigned cvt_pk_bf16(float lo, float hi) { unsigned r; asm volatile("v_cvt_pk_bf16_f32 %0, %1, %2" : "=v"(r) : "v"(lo), "v"(hi)); return r; }
; __device__ __forceinline__ float gelu_tanh(float x) {
;     const float u = x * (0.7978845608f + 0.0356774081f * x * x);
;     const float e = __builtin_amdgcn_exp2f(u * 2.8853900818f);
;     return x - x * __builtin_amdgcn_rcpf(e + 1.0f);
; }
;     __device__ __forceinline__ void operator()(const f32x4 (&acc)[2][2][4][2], const Unit& u, int wr, int wc, int fr, int fq) const {
;     ...
;                 for (int bj = 0; bj < 2; ++bj) { f32x4 v0 = acc[ai][bj][m][0] * rstd + bv[bj][0], v1 = acc[ai][bj][m][1] * rstd + bv[bj][1];
;                     if (ACT == 1) {
; #pragma unroll
;                         for (int e = 0; e < 4; ++e) { const float a = fmaxf(v0[e], 0.f), b2 = fmaxf(v1[e], 0.f); v0[e] = a * a; v1[e] = b2 * b2; } }
;                     if (ACT == 2) {
; #pragma unroll
;                         for (int e = 0; e < 4; ++e) { v0[e] = gelu_tanh(v0[e]); v1[e] = gelu_tanh(v1[e]); s += v0[e] + v1[e]; q += v0[e] * v0[e] + v1[e] * v1[e]; } }
;                     u32x4 w; w.x = cvt_pk_bf16(v0[0], v0[1]); w.y = cvt_pk_bf16(v0[2], v0[3]); w.z = cvt_pk_bf16(v1[0], v1[1]); w.w = cvt_pk_bf16(v1[2], v1[3]);
;                     *(u32x4*)(rowp + bj * HALF) = w; }
.LBB0_206:
	v_mul_f32_e32 v64, 0x4b800000, v80
	v_cndmask_b32_e64 v64, v80, v64, s[44:45]
	v_rsq_f32_e32 v64, v64
	s_and_b64 vcc, exec, s[42:43]
	v_mul_f32_e32 v65, 0x45800000, v64
	v_cndmask_b32_e64 v70, v64, v65, s[44:45]
	s_waitcnt lgkmcnt(0)
	v_fma_f32 v66, v58, v70, v42
	v_fma_f32 v67, v59, v70, v43
	v_fma_f32 v58, v56, v70, v40
	v_fma_f32 v59, v57, v70, v41
	v_fma_f32 v60, v60, v70, v44
	v_fma_f32 v61, v61, v70, v45
	v_mul_f32_e32 v57, 0x3d122279, v58
	v_fmaak_f32 v57, v58, v57, 0x3f4c422a
	v_mul_f32_e32 v57, v58, v57
	v_mul_f32_e32 v57, 0x4038aa3b, v57
	v_exp_f32_e32 v57, v57
	v_mul_f32_e32 v56, 0x3d122279, v60
	v_fmaak_f32 v56, v60, v56, 0x3f4c422a
	v_mul_f32_e32 v56, v60, v56
	v_add_f32_e32 v57, 1.0, v57
	v_rcp_f32_e32 v68, v57
	v_mul_f32_e32 v57, 0x3d122279, v61
	v_fmaak_f32 v57, v61, v57, 0x3f4c422a
	v_mul_f32_e32 v57, v61, v57
	v_mul_f32_e32 v56, 0x4038aa3b, v56
	v_mul_f32_e32 v57, 0x4038aa3b, v57
	v_exp_f32_e32 v56, v56
	v_exp_f32_e32 v57, v57
	v_mul_f32_e32 v69, 0x3d122279, v59
	v_fmaak_f32 v69, v59, v69, 0x3f4c422a
	v_add_f32_e32 v56, 1.0, v56
	v_add_f32_e32 v57, 1.0, v57
	v_rcp_f32_e32 v56, v56
	v_rcp_f32_e32 v57, v57
	v_mul_f32_e32 v69, v59, v69
	v_mul_f32_e32 v69, 0x4038aa3b, v69
	v_exp_f32_e32 v69, v69
	v_fma_f32 v56, -v60, v56, v60
	v_fma_f32 v57, -v61, v57, v61
	v_mul_f32_e32 v61, 0x3d122279, v66
	v_fmaak_f32 v61, v66, v61, 0x3f4c422a
	v_mul_f32_e32 v61, v66, v61
	v_mul_f32_e32 v61, 0x4038aa3b, v61
	v_add_f32_e32 v69, 1.0, v69
	v_exp_f32_e32 v61, v61
	v_rcp_f32_e32 v69, v69
	v_fma_f32 v62, v62, v70, v46
	v_fma_f32 v63, v63, v70, v47
	v_lshlrev_b64 v[64:65], 13, v[186:187]
	v_add_f32_e32 v61, 1.0, v61
	v_fma_f32 v58, -v58, v68, v58
	v_fma_f32 v59, -v59, v69, v59
	v_mul_f32_e32 v60, 0x3d122279, v62
	v_rcp_f32_e32 v68, v61
	v_mul_f32_e32 v61, 0x3d122279, v63
	v_mul_f32_e32 v69, 0x3d122279, v67
	v_fmaak_f32 v60, v62, v60, 0x3f4c422a
	v_fmaak_f32 v61, v63, v61, 0x3f4c422a
	v_fmaak_f32 v69, v67, v69, 0x3f4c422a
	v_mul_f32_e32 v60, v62, v60
	v_mul_f32_e32 v61, v63, v61
	v_mul_f32_e32 v69, v67, v69
	v_mul_f32_e32 v60, 0x4038aa3b, v60
	v_mul_f32_e32 v61, 0x4038aa3b, v61
	v_mul_f32_e32 v69, 0x4038aa3b, v69
	v_exp_f32_e32 v60, v60
	v_exp_f32_e32 v61, v61
	v_exp_f32_e32 v69, v69
	v_lshl_add_u64 v[64:65], s[2:3], 0, v[64:65]
	v_add_f32_e32 v60, 1.0, v60
	v_add_f32_e32 v61, 1.0, v61
	v_add_f32_e32 v69, 1.0, v69
	v_rcp_f32_e32 v60, v60
	v_rcp_f32_e32 v61, v61
	v_rcp_f32_e32 v69, v69
	v_lshl_add_u64 v[64:65], v[182:183], 1, v[64:65]
	v_fma_f32 v52, v52, v70, v36
	v_fma_f32 v53, v53, v70, v37
	v_fma_f32 v60, -v62, v60, v62
	v_fma_f32 v61, -v63, v61, v63
	v_fma_f32 v62, -v66, v68, v66
	v_fma_f32 v63, -v67, v69, v67
	v_cvt_pk_bf16_f32 v66, v56, v57
	v_cvt_pk_bf16_f32 v67, v60, v61
	v_cvt_pk_bf16_f32 v68, v58, v59
	v_fma_f32 v54, v54, v70, v38
	v_fma_f32 v55, v55, v70, v39
	v_cvt_pk_bf16_f32 v69, v62, v63
	global_store_dwordx4 v[64:65], v[66:69], off sc1
	s_nop 1
	v_fma_f32 v66, v50, v70, v34
	v_fma_f32 v67, v51, v70, v35
	v_fma_f32 v50, v48, v70, v32
	v_fma_f32 v51, v49, v70, v33
	v_mul_f32_e32 v48, 0x3d122279, v52
	v_mul_f32_e32 v49, 0x3d122279, v50
	v_fmaak_f32 v49, v50, v49, 0x3f4c422a
	v_mul_f32_e32 v49, v50, v49
	v_mul_f32_e32 v49, 0x4038aa3b, v49
	v_exp_f32_e32 v49, v49
	v_fmaak_f32 v48, v52, v48, 0x3f4c422a
	v_mul_f32_e32 v48, v52, v48
	v_mul_f32_e32 v48, 0x4038aa3b, v48
	v_add_f32_e32 v49, 1.0, v49
	v_rcp_f32_e32 v68, v49
	v_mul_f32_e32 v49, 0x3d122279, v53
	v_fmaak_f32 v49, v53, v49, 0x3f4c422a
	v_mul_f32_e32 v49, v53, v49
	v_mul_f32_e32 v49, 0x4038aa3b, v49
	v_exp_f32_e32 v48, v48
	v_exp_f32_e32 v49, v49
	v_mul_f32_e32 v69, 0x3d122279, v51
	v_fmaak_f32 v69, v51, v69, 0x3f4c422a
	v_add_f32_e32 v48, 1.0, v48
	v_add_f32_e32 v49, 1.0, v49
	v_rcp_f32_e32 v48, v48
	v_rcp_f32_e32 v49, v49
	v_mul_f32_e32 v69, v51, v69
	v_mul_f32_e32 v69, 0x4038aa3b, v69
	v_exp_f32_e32 v69, v69
	v_fma_f32 v48, -v52, v48, v52
	v_fma_f32 v49, -v53, v49, v53
	v_mul_f32_e32 v53, 0x3d122279, v66
	v_fmaak_f32 v53, v66, v53, 0x3f4c422a
	v_mul_f32_e32 v53, v66, v53
	v_mul_f32_e32 v53, 0x4038aa3b, v53
	v_add_f32_e32 v69, 1.0, v69
	v_exp_f32_e32 v53, v53
	v_rcp_f32_e32 v69, v69
	v_mul_f32_e32 v52, 0x3d122279, v54
	v_mov_b32_e32 v70, v66
	v_add_f32_e32 v53, 1.0, v53
	v_fma_f32 v50, -v50, v68, v50
	v_fma_f32 v51, -v51, v69, v51
	v_rcp_f32_e32 v68, v53
	v_mul_f32_e32 v53, 0x3d122279, v55
	v_fmaak_f32 v53, v55, v53, 0x3f4c422a
	v_mul_f32_e32 v66, 0x3d122279, v67
	v_fmaak_f32 v52, v54, v52, 0x3f4c422a
	v_mul_f32_e32 v53, v55, v53
	v_fmaak_f32 v66, v67, v66, 0x3f4c422a
	v_mul_f32_e32 v52, v54, v52
	v_mul_f32_e32 v53, 0x4038aa3b, v53
	v_mul_f32_e32 v66, v67, v66
	v_mul_f32_e32 v52, 0x4038aa3b, v52
	v_exp_f32_e32 v53, v53
	v_mul_f32_e32 v66, 0x4038aa3b, v66
	v_exp_f32_e32 v52, v52
	v_exp_f32_e32 v66, v66
	v_add_f32_e32 v53, 1.0, v53
	v_rcp_f32_e32 v53, v53
	v_add_f32_e32 v52, 1.0, v52
	v_add_f32_e32 v66, 1.0, v66
	v_rcp_f32_e32 v52, v52
	v_rcp_f32_e32 v66, v66
	v_mov_b32_e32 v71, v55
	v_mov_b32_e32 v69, v53
	v_fma_f32 v52, -v54, v52, v54
	v_fma_f32 v53, -v55, v53, v55
	v_fma_f32 v54, -v70, v68, v70
	v_fma_f32 v55, -v71, v69, v71
	v_fma_f32 v66, -v67, v66, v67
	v_cvt_pk_bf16_f32 v68, v48, v49
	v_cvt_pk_bf16_f32 v69, v52, v53
	v_cvt_pk_bf16_f32 v70, v50, v51
	v_cvt_pk_bf16_f32 v71, v54, v66
	global_store_dwordx4 v[64:65], v[68:71], off offset:256 sc1
	s_cbranch_vccnz .LBB0_210
; __device__ __forceinline__ unsigned cvt_pk_bf16(float lo, float hi) { unsigned r; asm volatile("v_cvt_pk_bf16_f32 %0, %1, %2" : "=v"(r) : "v"(lo), "v"(hi)); return r; }
;     __device__ __forceinline__ void operator()(const f32x4 (&acc)[2][2][4][2], const Unit& u, int wr, int wc, int fr, int fq) const {
;     ...
;                         for (int e = 0; e < 4; ++e) { v0[e] = gelu_tanh(v0[e]); v1[e] = gelu_tanh(v1[e]); s += v0[e] + v1[e]; q += v0[e] * v0[e] + v1[e] * v1[e]; } }
;                     u32x4 w; w.x = cvt_pk_bf16(v0[0], v0[1]); w.y = cvt_pk_bf16(v0[2], v0[3]); w.z = cvt_pk_bf16(v1[0], v1[1]); w.w = cvt_pk_bf16(v1[2], v1[3]);
;                     *(u32x4*)(rowp + bj * HALF) = w; }
;                 if (ACT == 2) { if (u.pn >= 8) { s += __shfl_xor(s, 16); s += __shfl_xor(s, 32); q += __shfl_xor(q, 16); q += __shfl_xor(q, 32);
;                     if (fq == 0) *(f32x2*)(stats + ((size_t)row * 32 + (u.pn - 8) * 4 + wc) * 2) = (f32x2){s, q}; } }
	v_mul_f32_e32 v64, v58, v58
	v_mul_f32_e32 v65, v59, v59
	v_mul_f32_e32 v68, v62, v62
	v_mul_f32_e32 v69, v63, v63
	v_fma_f32 v64, v56, v56, v64
	v_fma_f32 v65, v57, v57, v65
	v_fma_f32 v68, v60, v60, v68
	v_fma_f32 v69, v61, v61, v69
	v_add_f32_e32 v64, v64, v65
	v_mul_f32_e32 v70, v50, v50
	v_mul_f32_e32 v71, v51, v51
	v_add_f32_e32 v64, v68, v64
	v_fma_f32 v70, v48, v48, v70
	v_fma_f32 v71, v49, v49, v71
	v_add_f32_e32 v64, v69, v64
	v_add_f32_e32 v64, v70, v64
	v_add_f32_e32 v65, v71, v64
	v_add_f32_e32 v64, v70, v64
	v_add_f32_e32 v56, v56, v58
	v_add_f32_e32 v57, v57, v59
	v_mov_b32_e32 v68, v52
	v_mov_b32_e32 v69, v54
	v_mul_f32_e32 v64, v52, v52
	v_add_f32_e32 v70, v52, v54
	v_add_f32_e32 v71, v53, v55
	v_mul_f32_e32 v54, v52, v54
	v_mul_f32_e32 v55, v53, v55
	v_add_f32_e32 v52, 0, v56
	v_add_f32_e32 v52, v57, v52
	v_add_f32_e32 v56, v60, v62
	v_add_f32_e32 v57, v61, v63
	v_add_f32_e32 v48, v48, v50
	v_add_f32_e32 v49, v49, v51
	v_add_f32_e32 v52, v56, v52
	v_add_f32_e32 v52, v57, v52
	v_fma_f32 v68, v68, v68, v64
	v_fma_f32 v69, v69, v69, v64
	v_add_f32_e32 v48, v48, v52
	v_mov_b32_e32 v71, v55
	v_mul_f32_e32 v55, v66, v66
	v_add_f32_e32 v54, v49, v48
	v_mov_b32_e32 v68, v53
	v_mov_b32_e32 v67, v65
	v_add_f32_e32 v48, v70, v54
	v_add_f32_e32 v49, v71, v55
	v_add_f32_e32 v50, v68, v66
	v_add_f32_e32 v51, v69, v67
	s_nop 0
	v_add_f32_e32 v48, v48, v50
	v_add_f32_e32 v49, v49, v51
	ds_bpermute_b32 v50, v205, v48
	ds_bpermute_b32 v51, v205, v49
	s_waitcnt lgkmcnt(0)
	v_add_f32_e32 v48, v48, v50
	v_add_f32_e32 v49, v49, v51
	ds_bpermute_b32 v50, v206, v48
	ds_bpermute_b32 v51, v206, v49
	s_and_saveexec_b64 s[44:45], s[38:39]
	s_cbranch_execz .LBB0_209
	v_lshlrev_b64 v[52:53], 8, v[186:187]
	s_waitcnt lgkmcnt(0)
	v_add_f32_e32 v48, v48, v50
	v_add_f32_e32 v49, v49, v51
	v_lshl_add_u64 v[50:51], s[6:7], 0, v[52:53]
	v_lshl_add_u64 v[50:51], s[36:37], 3, v[50:51]
	global_store_dwordx2 v[50:51], v[48:49], off

; __device__ __forceinline__ unsigned cvt_pk_bf16(float lo, float hi) { unsigned r; asm volatile("v_cvt_pk_bf16_f32 %0, %1, %2" : "=v"(r) : "v"(lo), "v"(hi)); return r; }
; __device__ __forceinline__ float gelu_tanh(float x) {
;     const float u = x * (0.7978845608f + 0.0356774081f * x * x);
;     const float e = __builtin_amdgcn_exp2f(u * 2.8853900818f);
;     return x - x * __builtin_amdgcn_rcpf(e + 1.0f);
; }
;     __device__ __forceinline__ void operator()(const f32x4 (&acc)[2][2][4][2], const Unit& u, int wr, int wc, int fr, int fq) const {
;     ...
;               for (int m = 0; m < 4; ++m) { float t = (pq[ai][m][0] + pq[ai][m][1]) + (pq[ai][m][2] + pq[ai][m][3]); t += __shfl_xor(t, 16); t += __shfl_xor(t, 32);
;                   rsv[ai][m] = rsqrtf(t * (1.f / DM) + EPS); } }
; #pragma unroll
;         for (int ai = 0; ai < 2; ++ai)
; #pragma unroll
;             for (int m = 0; m < 4; ++m) { const int row = row0 + ai * HALF + m * 16; bf16_t* rowp = O + (size_t)row * ldc + col0; float s = 0.f, q = 0.f;
;                 const float rstd = rsv[ai][m];
; #pragma unroll
;                 for (int bj = 0; bj < 2; ++bj) { f32x4 v0 = acc[ai][bj][m][0] * rstd + bv[bj][0], v1 = acc[ai][bj][m][1] * rstd + bv[bj][1];
;                     if (ACT == 1) {
; #pragma unroll
;                         for (int e = 0; e < 4; ++e) { const float a = fmaxf(v0[e], 0.f), b2 = fmaxf(v1[e], 0.f); v0[e] = a * a; v1[e] = b2 * b2; } }
;                     if (ACT == 2) {
; #pragma unroll
;                         for (int e = 0; e < 4; ++e) { v0[e] = gelu_tanh(v0[e]); v1[e] = gelu_tanh(v1[e]); s += v0[e] + v1[e]; q += v0[e] * v0[e] + v1[e] * v1[e]; } }
;                     u32x4 w; w.x = cvt_pk_bf16(v0[0], v0[1]); w.y = cvt_pk_bf16(v0[2], v0[3]); w.z = cvt_pk_bf16(v1[0], v1[1]); w.w = cvt_pk_bf16(v1[2], v1[3]);
;                     *(u32x4*)(rowp + bj * HALF) = w; }
.LBB0_210:
	v_add_f32_e32 v48, v144, v146
	v_add_f32_e32 v49, v145, v147
	s_nop 0
	v_fma_f32 v48, v48, s16, v214
	v_fma_f32 v49, v49, s16, v214
	s_waitcnt lgkmcnt(1)
	v_mul_f32_e32 v50, 0x4b800000, v49
	v_cmp_gt_f32_e32 vcc, s27, v49
	v_cmp_gt_f32_e64 s[44:45], s27, v48
	s_nop 0
	v_cndmask_b32_e32 v49, v49, v50, vcc
	v_rsq_f32_e32 v49, v49
	s_nop 0
	v_mul_f32_e32 v50, 0x45800000, v49
	v_cndmask_b32_e32 v56, v49, v50, vcc
	v_fma_f32 v52, v26, v56, v42
	v_fma_f32 v53, v27, v56, v43
	v_fma_f32 v26, v24, v56, v40
	v_fma_f32 v27, v25, v56, v41
	v_fma_f32 v28, v28, v56, v44
	v_fma_f32 v29, v29, v56, v45
	v_mul_f32_e32 v25, 0x3d122279, v26
	v_fmaak_f32 v25, v26, v25, 0x3f4c422a
	v_mul_f32_e32 v25, v26, v25
	v_mul_f32_e32 v25, 0x4038aa3b, v25
	v_exp_f32_e32 v25, v25
	v_mul_f32_e32 v24, 0x3d122279, v28
	v_fmaak_f32 v24, v28, v24, 0x3f4c422a
	v_mul_f32_e32 v24, v28, v24
	v_add_f32_e32 v25, 1.0, v25
	v_rcp_f32_e32 v54, v25
	v_mul_f32_e32 v25, 0x3d122279, v29
	v_fmaak_f32 v25, v29, v25, 0x3f4c422a
	v_mul_f32_e32 v25, v29, v25
	v_mul_f32_e32 v24, 0x4038aa3b, v24
	v_mul_f32_e32 v25, 0x4038aa3b, v25
	v_exp_f32_e32 v24, v24
	v_exp_f32_e32 v25, v25
	v_mul_f32_e32 v49, 0x3d122279, v27
	v_fmaak_f32 v49, v27, v49, 0x3f4c422a
	v_add_f32_e32 v24, 1.0, v24
	v_add_f32_e32 v25, 1.0, v25
	v_rcp_f32_e32 v24, v24
	v_rcp_f32_e32 v25, v25
	v_mul_f32_e32 v49, v27, v49
	v_mul_f32_e32 v49, 0x4038aa3b, v49
	v_exp_f32_e32 v49, v49
	v_fma_f32 v24, -v28, v24, v28
	v_fma_f32 v25, -v29, v25, v29
	v_mul_f32_e32 v29, 0x3d122279, v52
	v_fmaak_f32 v29, v52, v29, 0x3f4c422a
	v_mul_f32_e32 v29, v52, v29
	v_mul_f32_e32 v29, 0x4038aa3b, v29
	v_add_f32_e32 v49, 1.0, v49
	v_exp_f32_e32 v29, v29
	v_rcp_f32_e32 v55, v49
	v_fma_f32 v30, v30, v56, v46
	v_fma_f32 v31, v31, v56, v47
	v_mul_f32_e32 v49, 0x3d122279, v53
	v_add_f32_e32 v29, 1.0, v29
	v_fma_f32 v26, -v26, v54, v26
	v_fma_f32 v27, -v27, v55, v27
	v_mul_f32_e32 v28, 0x3d122279, v30
	v_rcp_f32_e32 v54, v29
	v_mul_f32_e32 v29, 0x3d122279, v31
	v_fmaak_f32 v28, v30, v28, 0x3f4c422a
	v_fmaak_f32 v29, v31, v29, 0x3f4c422a
	v_fmaak_f32 v49, v53, v49, 0x3f4c422a
	v_mul_f32_e32 v28, v30, v28
	v_mul_f32_e32 v29, v31, v29
	v_mul_f32_e32 v49, v53, v49
	v_mul_f32_e32 v28, 0x4038aa3b, v28
	v_mul_f32_e32 v29, 0x4038aa3b, v29
	v_mul_f32_e32 v49, 0x4038aa3b, v49
	v_exp_f32_e32 v28, v28
	v_exp_f32_e32 v29, v29
	v_exp_f32_e32 v49, v49
	s_waitcnt lgkmcnt(0)
	v_lshlrev_b64 v[50:51], 13, v[184:185]
	v_add_f32_e32 v28, 1.0, v28
	v_add_f32_e32 v29, 1.0, v29
	v_add_f32_e32 v49, 1.0, v49
	v_rcp_f32_e32 v28, v28
	v_rcp_f32_e32 v29, v29
	v_rcp_f32_e32 v55, v49
	v_lshl_add_u64 v[50:51], s[2:3], 0, v[50:51]
	v_lshl_add_u64 v[50:51], v[182:183], 1, v[50:51]
	v_fma_f32 v28, -v30, v28, v30
	v_fma_f32 v29, -v31, v29, v31
	v_fma_f32 v30, -v52, v54, v52
	v_fma_f32 v31, -v53, v55, v53
	v_cvt_pk_bf16_f32 v52, v24, v25
	v_cvt_pk_bf16_f32 v53, v28, v29
	v_cvt_pk_bf16_f32 v54, v26, v27
	v_fma_f32 v20, v20, v56, v36
	v_fma_f32 v21, v21, v56, v37
	v_cvt_pk_bf16_f32 v55, v30, v31
	global_store_dwordx4 v[50:51], v[52:55], off sc1
	v_fma_f32 v22, v22, v56, v38
	v_fma_f32 v23, v23, v56, v39
	s_and_b64 vcc, exec, s[42:43]
	v_fma_f32 v52, v18, v56, v34
	v_fma_f32 v53, v19, v56, v35
	v_fma_f32 v18, v16, v56, v32
	v_fma_f32 v19, v17, v56, v33
	v_mul_f32_e32 v16, 0x3d122279, v20
	v_mul_f32_e32 v17, 0x3d122279, v18
	v_fmaak_f32 v17, v18, v17, 0x3f4c422a
	v_mul_f32_e32 v17, v18, v17
	v_mul_f32_e32 v17, 0x4038aa3b, v17
	v_exp_f32_e32 v17, v17
	v_fmaak_f32 v16, v20, v16, 0x3f4c422a
	v_mul_f32_e32 v16, v20, v16
	v_mul_f32_e32 v16, 0x4038aa3b, v16
	v_add_f32_e32 v17, 1.0, v17
	v_rcp_f32_e32 v54, v17
	v_mul_f32_e32 v17, 0x3d122279, v21
	v_fmaak_f32 v17, v21, v17, 0x3f4c422a
	v_mul_f32_e32 v17, v21, v17
	v_mul_f32_e32 v17, 0x4038aa3b, v17
	v_exp_f32_e32 v16, v16
	v_exp_f32_e32 v17, v17
	v_mul_f32_e32 v49, 0x3d122279, v19
	v_fmaak_f32 v49, v19, v49, 0x3f4c422a
	v_add_f32_e32 v16, 1.0, v16
	v_add_f32_e32 v17, 1.0, v17
	v_rcp_f32_e32 v16, v16
	v_rcp_f32_e32 v17, v17
	v_mul_f32_e32 v49, v19, v49
	v_mul_f32_e32 v49, 0x4038aa3b, v49
	v_exp_f32_e32 v49, v49
	v_fma_f32 v16, -v20, v16, v20
	v_fma_f32 v17, -v21, v17, v21
	v_mul_f32_e32 v21, 0x3d122279, v52
	v_fmaak_f32 v21, v52, v21, 0x3f4c422a
	v_mul_f32_e32 v21, v52, v21
	v_mul_f32_e32 v21, 0x4038aa3b, v21
	v_add_f32_e32 v49, 1.0, v49
	v_exp_f32_e32 v21, v21
	v_rcp_f32_e32 v55, v49
	v_mul_f32_e32 v20, 0x3d122279, v22
	v_mul_f32_e32 v49, 0x3d122279, v53
	v_add_f32_e32 v21, 1.0, v21
	v_fma_f32 v18, -v18, v54, v18
	v_fma_f32 v19, -v19, v55, v19
	v_rcp_f32_e32 v54, v21
	v_mul_f32_e32 v21, 0x3d122279, v23
	v_fmaak_f32 v21, v23, v21, 0x3f4c422a
	v_fmaak_f32 v20, v22, v20, 0x3f4c422a
	v_mul_f32_e32 v21, v23, v21
	v_fmaak_f32 v49, v53, v49, 0x3f4c422a
	v_mul_f32_e32 v20, v22, v20
	v_mul_f32_e32 v21, 0x4038aa3b, v21
	v_mul_f32_e32 v49, v53, v49
	v_mul_f32_e32 v20, 0x4038aa3b, v20
	v_exp_f32_e32 v21, v21
	v_mul_f32_e32 v49, 0x4038aa3b, v49
	v_exp_f32_e32 v20, v20
	v_exp_f32_e32 v49, v49
	v_add_f32_e32 v21, 1.0, v21
	v_rcp_f32_e32 v21, v21
	v_add_f32_e32 v20, 1.0, v20
	v_add_f32_e32 v49, 1.0, v49
	v_rcp_f32_e32 v20, v20
	v_rcp_f32_e32 v49, v49
	v_mov_b32_e32 v56, v52
	v_mov_b32_e32 v57, v23
	v_mov_b32_e32 v55, v21
	v_fma_f32 v20, -v22, v20, v22
	v_fma_f32 v21, -v23, v21, v23
	v_fma_f32 v22, -v56, v54, v56
	v_fma_f32 v23, -v57, v55, v57
	v_fma_f32 v52, -v53, v49, v53
	v_cvt_pk_bf16_f32 v54, v16, v17
	v_cvt_pk_bf16_f32 v55, v20, v21
	v_cvt_pk_bf16_f32 v56, v18, v19
	v_cvt_pk_bf16_f32 v57, v22, v52
	global_store_dwordx4 v[50:51], v[54:57], off offset:256 sc1
	s_cbranch_vccnz .LBB0_214
; __device__ __forceinline__ unsigned cvt_pk_bf16(float lo, float hi) { unsigned r; asm volatile("v_cvt_pk_bf16_f32 %0, %1, %2" : "=v"(r) : "v"(lo), "v"(hi)); return r; }
;     __device__ __forceinline__ void operator()(const f32x4 (&acc)[2][2][4][2], const Unit& u, int wr, int wc, int fr, int fq) const {
;     ...
;                         for (int e = 0; e < 4; ++e) { v0[e] = gelu_tanh(v0[e]); v1[e] = gelu_tanh(v1[e]); s += v0[e] + v1[e]; q += v0[e] * v0[e] + v1[e] * v1[e]; } }
;                     u32x4 w; w.x = cvt_pk_bf16(v0[0], v0[1]); w.y = cvt_pk_bf16(v0[2], v0[3]); w.z = cvt_pk_bf16(v1[0], v1[1]); w.w = cvt_pk_bf16(v1[2], v1[3]);
;                     *(u32x4*)(rowp + bj * HALF) = w; }
;                 if (ACT == 2) { if (u.pn >= 8) { s += __shfl_xor(s, 16); s += __shfl_xor(s, 32); q += __shfl_xor(q, 16); q += __shfl_xor(q, 32);
;                     if (fq == 0) *(f32x2*)(stats + ((size_t)row * 32 + (u.pn - 8) * 4 + wc) * 2) = (f32x2){s, q}; } }
	v_mul_f32_e32 v50, v26, v26
	v_mul_f32_e32 v51, v27, v27
	v_mul_f32_e32 v54, v30, v30
	v_mul_f32_e32 v55, v31, v31
	v_fma_f32 v50, v24, v24, v50
	v_fma_f32 v51, v25, v25, v51
	v_fma_f32 v54, v28, v28, v54
	v_fma_f32 v55, v29, v29, v55
	v_add_f32_e32 v49, v50, v51
	v_mul_f32_e32 v56, v18, v18
	v_mul_f32_e32 v57, v19, v19
	v_add_f32_e32 v49, v54, v49
	v_fma_f32 v56, v16, v16, v56
	v_fma_f32 v57, v17, v17, v57
	v_add_f32_e32 v49, v55, v49
	v_add_f32_e32 v50, v56, v49
	v_add_f32_e32 v51, v57, v50
	v_add_f32_e32 v50, v56, v50
	v_add_f32_e32 v24, v24, v26
	v_add_f32_e32 v25, v25, v27
	v_mov_b32_e32 v54, v20
	v_mov_b32_e32 v55, v22
	v_mul_f32_e32 v50, v20, v20
	v_add_f32_e32 v56, v20, v22
	v_add_f32_e32 v57, v21, v23
	v_mul_f32_e32 v22, v20, v22
	v_mul_f32_e32 v23, v21, v23
	v_add_f32_e32 v20, 0, v24
	v_add_f32_e32 v20, v25, v20
	v_add_f32_e32 v24, v28, v30
	v_add_f32_e32 v25, v29, v31
	v_add_f32_e32 v16, v16, v18
	v_add_f32_e32 v17, v17, v19
	v_add_f32_e32 v20, v24, v20
	v_add_f32_e32 v20, v25, v20
	v_fma_f32 v54, v54, v54, v50
	v_fma_f32 v55, v55, v55, v50
	v_add_f32_e32 v16, v16, v20
	v_mov_b32_e32 v57, v23
	v_mul_f32_e32 v23, v52, v52
	v_add_f32_e32 v22, v17, v16
	v_mov_b32_e32 v54, v21
	v_mov_b32_e32 v53, v51
	v_add_f32_e32 v16, v56, v22
	v_add_f32_e32 v17, v57, v23
	v_add_f32_e32 v18, v54, v52
	v_add_f32_e32 v19, v55, v53
	s_nop 0
	v_add_f32_e32 v16, v16, v18
	v_add_f32_e32 v17, v17, v19
	ds_bpermute_b32 v18, v205, v16
	ds_bpermute_b32 v19, v205, v17
	s_waitcnt lgkmcnt(0)
	v_add_f32_e32 v16, v16, v18
	v_add_f32_e32 v17, v17, v19
	ds_bpermute_b32 v18, v206, v16
	ds_bpermute_b32 v19, v206, v17
	s_and_saveexec_b64 s[46:47], s[38:39]
	s_cbranch_execz .LBB0_213
	v_lshlrev_b64 v[20:21], 8, v[184:185]
	s_waitcnt lgkmcnt(0)
	v_add_f32_e32 v16, v16, v18
	v_add_f32_e32 v17, v17, v19
	v_lshl_add_u64 v[18:19], s[6:7], 0, v[20:21]
	v_lshl_add_u64 v[18:19], s[36:37], 3, v[18:19]
	global_store_dwordx2 v[18:19], v[16:17], off

; __device__ __forceinline__ unsigned cvt_pk_bf16(float lo, float hi) { unsigned r; asm volatile("v_cvt_pk_bf16_f32 %0, %1, %2" : "=v"(r) : "v"(lo), "v"(hi)); return r; }
; __device__ __forceinline__ float gelu_tanh(float x) {
;     const float u = x * (0.7978845608f + 0.0356774081f * x * x);
;     const float e = __builtin_amdgcn_exp2f(u * 2.8853900818f);
;     return x - x * __builtin_amdgcn_rcpf(e + 1.0f);
; }
;     __device__ __forceinline__ void operator()(const f32x4 (&acc)[2][2][4][2], const Unit& u, int wr, int wc, int fr, int fq) const {
;     ...
;                 for (int bj = 0; bj < 2; ++bj) { f32x4 v0 = acc[ai][bj][m][0] * rstd + bv[bj][0], v1 = acc[ai][bj][m][1] * rstd + bv[bj][1];
;                     if (ACT == 1) {
; #pragma unroll
;                         for (int e = 0; e < 4; ++e) { const float a = fmaxf(v0[e], 0.f), b2 = fmaxf(v1[e], 0.f); v0[e] = a * a; v1[e] = b2 * b2; } }
;                     if (ACT == 2) {
; #pragma unroll
;                         for (int e = 0; e < 4; ++e) { v0[e] = gelu_tanh(v0[e]); v1[e] = gelu_tanh(v1[e]); s += v0[e] + v1[e]; q += v0[e] * v0[e] + v1[e] * v1[e]; } }
;                     u32x4 w; w.x = cvt_pk_bf16(v0[0], v0[1]); w.y = cvt_pk_bf16(v0[2], v0[3]); w.z = cvt_pk_bf16(v1[0], v1[1]); w.w = cvt_pk_bf16(v1[2], v1[3]);
;                     *(u32x4*)(rowp + bj * HALF) = w; }
.LBB0_214:
	v_mul_f32_e32 v16, 0x4b800000, v48
	v_cndmask_b32_e64 v16, v48, v16, s[44:45]
	s_waitcnt lgkmcnt(1)
	v_rsq_f32_e32 v18, v16
	v_lshlrev_b64 v[16:17], 13, v[180:181]
	v_lshl_add_u64 v[16:17], s[2:3], 0, v[16:17]
	v_lshl_add_u64 v[22:23], v[182:183], 1, v[16:17]
	v_mul_f32_e32 v16, 0x45800000, v18
	v_cndmask_b32_e64 v20, v18, v16, s[44:45]
	v_fma_f32 v12, v12, v20, v44
	v_fma_f32 v13, v13, v20, v45
	s_waitcnt lgkmcnt(0)
	v_fma_f32 v18, v10, v20, v42
	v_fma_f32 v19, v11, v20, v43
	v_mul_f32_e32 v10, 0x3d122279, v13
	v_fmaak_f32 v10, v13, v10, 0x3f4c422a
	v_fma_f32 v16, v8, v20, v40
	v_fma_f32 v17, v9, v20, v41
	v_mul_f32_e32 v10, v13, v10
	v_mul_f32_e32 v9, 0x3d122279, v16
	v_mul_f32_e32 v10, 0x4038aa3b, v10
	v_fmaak_f32 v9, v16, v9, 0x3f4c422a
	v_exp_f32_e32 v11, v10
	v_mul_f32_e32 v10, 0x3d122279, v17
	v_mul_f32_e32 v9, v16, v9
	v_fmaak_f32 v10, v17, v10, 0x3f4c422a
	v_mul_f32_e32 v9, 0x4038aa3b, v9
	v_mul_f32_e32 v10, v17, v10
	v_exp_f32_e32 v9, v9
	v_mul_f32_e32 v10, 0x4038aa3b, v10
	v_fma_f32 v14, v14, v20, v46
	v_fma_f32 v15, v15, v20, v47
	v_exp_f32_e32 v21, v10
	v_add_f32_e32 v9, 1.0, v9
	v_rcp_f32_e32 v10, v9
	v_add_f32_e32 v9, 1.0, v11
	v_add_f32_e32 v11, 1.0, v21
	v_mul_f32_e32 v21, 0x3d122279, v14
	v_fmaak_f32 v21, v14, v21, 0x3f4c422a
	v_mul_f32_e32 v24, 0x3d122279, v18
	v_mul_f32_e32 v21, v14, v21
	v_fmaak_f32 v24, v18, v24, 0x3f4c422a
	v_mul_f32_e32 v21, 0x4038aa3b, v21
	v_mul_f32_e32 v24, v18, v24
	v_exp_f32_e32 v21, v21
	v_mul_f32_e32 v24, 0x4038aa3b, v24
	v_exp_f32_e32 v25, v24
	v_mul_f32_e32 v8, 0x3d122279, v12
	v_add_f32_e32 v21, 1.0, v21
	v_rcp_f32_e32 v24, v21
	v_add_f32_e32 v21, 1.0, v25
	v_mul_f32_e32 v25, 0x3d122279, v15
	v_fmaak_f32 v25, v15, v25, 0x3f4c422a
	v_mul_f32_e32 v26, 0x3d122279, v19
	v_fmaak_f32 v8, v12, v8, 0x3f4c422a
	v_mul_f32_e32 v25, v15, v25
	v_fmaak_f32 v26, v19, v26, 0x3f4c422a
	v_mul_f32_e32 v8, v12, v8
	v_mul_f32_e32 v25, 0x4038aa3b, v25
	v_mul_f32_e32 v26, v19, v26
	v_mul_f32_e32 v8, 0x4038aa3b, v8
	v_exp_f32_e32 v25, v25
	v_mul_f32_e32 v26, 0x4038aa3b, v26
	v_exp_f32_e32 v8, v8
	v_exp_f32_e32 v27, v26
	v_rcp_f32_e32 v26, v21
	v_add_f32_e32 v21, 1.0, v25
	v_add_f32_e32 v8, 1.0, v8
	v_rcp_f32_e32 v25, v21
	v_add_f32_e32 v21, 1.0, v27
	v_rcp_f32_e32 v8, v8
	v_rcp_f32_e32 v9, v9
	v_rcp_f32_e32 v11, v11
	v_rcp_f32_e32 v27, v21
	v_fma_f32 v4, v4, v20, v36
	v_fma_f32 v5, v5, v20, v37
	v_fma_f32 v8, -v12, v8, v12
	v_fma_f32 v9, -v13, v9, v13
	v_fma_f32 v10, -v16, v10, v16
	v_fma_f32 v11, -v17, v11, v17
	v_fma_f32 v12, -v14, v24, v14
	v_fma_f32 v13, -v15, v25, v15
	v_fma_f32 v14, -v18, v26, v18
	v_fma_f32 v15, -v19, v27, v19
	v_cvt_pk_bf16_f32 v16, v8, v9
	v_cvt_pk_bf16_f32 v17, v12, v13
	v_cvt_pk_bf16_f32 v18, v10, v11
	v_fma_f32 v6, v6, v20, v38
	v_fma_f32 v7, v7, v20, v39
	v_cvt_pk_bf16_f32 v19, v14, v15
	global_store_dwordx4 v[22:23], v[16:19], off sc1
	s_and_b64 vcc, exec, s[42:43]
	s_nop 0
	v_mul_f32_e32 v18, 0x3d122279, v5
	v_fmaak_f32 v18, v5, v18, 0x3f4c422a
	v_fma_f32 v16, v0, v20, v32
	v_fma_f32 v17, v1, v20, v33
	v_mul_f32_e32 v18, v5, v18
	v_mul_f32_e32 v1, 0x3d122279, v16
	v_mul_f32_e32 v18, 0x4038aa3b, v18
	v_mul_f32_e32 v0, 0x3d122279, v4
	v_fmaak_f32 v1, v16, v1, 0x3f4c422a
	v_exp_f32_e32 v19, v18
	v_mul_f32_e32 v18, 0x3d122279, v17
	v_fmaak_f32 v0, v4, v0, 0x3f4c422a
	v_mul_f32_e32 v1, v16, v1
	v_fmaak_f32 v18, v17, v18, 0x3f4c422a
	v_mul_f32_e32 v0, v4, v0
	v_mul_f32_e32 v1, 0x4038aa3b, v1
	v_mul_f32_e32 v18, v17, v18
	v_mul_f32_e32 v0, 0x4038aa3b, v0
	v_exp_f32_e32 v1, v1
	v_mul_f32_e32 v18, 0x4038aa3b, v18
	v_exp_f32_e32 v0, v0
	v_exp_f32_e32 v21, v18
	v_add_f32_e32 v1, 1.0, v1
	v_rcp_f32_e32 v18, v1
	v_add_f32_e32 v0, 1.0, v0
	v_add_f32_e32 v1, 1.0, v19
	v_add_f32_e32 v19, 1.0, v21
	v_mul_f32_e32 v21, 0x3d122279, v6
	v_rcp_f32_e32 v0, v0
	v_rcp_f32_e32 v1, v1
	v_fmaak_f32 v21, v6, v21, 0x3f4c422a
	v_rcp_f32_e32 v19, v19
	v_mul_f32_e32 v21, v6, v21
	v_mul_f32_e32 v21, 0x4038aa3b, v21
	v_exp_f32_e32 v24, v21
	v_fma_f32 v21, v3, v20, v35
	v_fma_f32 v20, v2, v20, v34
	v_fma_f32 v0, -v4, v0, v4
	v_fma_f32 v1, -v5, v1, v5
	v_mul_f32_e32 v5, 0x3d122279, v20
	v_fma_f32 v2, -v16, v18, v16
	v_fma_f32 v3, -v17, v19, v17
	v_fmaak_f32 v5, v20, v5, 0x3f4c422a
	v_mul_f32_e32 v16, 0x3d122279, v7
	v_mul_f32_e32 v5, v20, v5
	v_fmaak_f32 v16, v7, v16, 0x3f4c422a
	v_mul_f32_e32 v5, 0x4038aa3b, v5
	v_mul_f32_e32 v16, v7, v16
	v_exp_f32_e32 v5, v5
	v_mul_f32_e32 v16, 0x4038aa3b, v16
	v_exp_f32_e32 v17, v16
	v_add_f32_e32 v4, 1.0, v24
	v_add_f32_e32 v5, 1.0, v5
	v_rcp_f32_e32 v16, v5
	v_add_f32_e32 v5, 1.0, v17
	v_mul_f32_e32 v17, 0x3d122279, v21
	v_fmaak_f32 v17, v21, v17, 0x3f4c422a
	v_mul_f32_e32 v17, v21, v17
	v_mul_f32_e32 v17, 0x4038aa3b, v17
	v_exp_f32_e32 v17, v17
	v_rcp_f32_e32 v5, v5
	v_rcp_f32_e32 v4, v4
	v_mov_b32_e32 v18, v20
	v_add_f32_e32 v17, 1.0, v17
	v_rcp_f32_e32 v20, v17
	v_mov_b32_e32 v19, v7
	v_mov_b32_e32 v17, v5
	v_fma_f32 v6, -v6, v4, v6
	v_fma_f32 v7, -v7, v5, v7
	v_fma_f32 v16, -v18, v16, v18
	v_fma_f32 v17, -v19, v17, v19
	v_fma_f32 v4, -v21, v20, v21
	v_cvt_pk_bf16_f32 v18, v0, v1
	v_cvt_pk_bf16_f32 v19, v6, v7
	v_cvt_pk_bf16_f32 v20, v2, v3
	v_cvt_pk_bf16_f32 v21, v16, v4
	global_store_dwordx4 v[22:23], v[18:21], off offset:256 sc1
	s_cbranch_vccnz .LBB0_218
; __device__ __forceinline__ unsigned cvt_pk_bf16(float lo, float hi) { unsigned r; asm volatile("v_cvt_pk_bf16_f32 %0, %1, %2" : "=v"(r) : "v"(lo), "v"(hi)); return r; }
;     __device__ __forceinline__ void operator()(const f32x4 (&acc)[2][2][4][2], const Unit& u, int wr, int wc, int fr, int fq) const {
;     ...
;                         for (int e = 0; e < 4; ++e) { v0[e] = gelu_tanh(v0[e]); v1[e] = gelu_tanh(v1[e]); s += v0[e] + v1[e]; q += v0[e] * v0[e] + v1[e] * v1[e]; } }
;                     u32x4 w; w.x = cvt_pk_bf16(v0[0], v0[1]); w.y = cvt_pk_bf16(v0[2], v0[3]); w.z = cvt_pk_bf16(v1[0], v1[1]); w.w = cvt_pk_bf16(v1[2], v1[3]);
;                     *(u32x4*)(rowp + bj * HALF) = w; }
;                 if (ACT == 2) { if (u.pn >= 8) { s += __shfl_xor(s, 16); s += __shfl_xor(s, 32); q += __shfl_xor(q, 16); q += __shfl_xor(q, 32);
;                     if (fq == 0) *(f32x2*)(stats + ((size_t)row * 32 + (u.pn - 8) * 4 + wc) * 2) = (f32x2){s, q}; } }
	s_nop 0
	v_mul_f32_e32 v18, v10, v10
	v_mul_f32_e32 v19, v11, v11
	v_mul_f32_e32 v20, v14, v14
	v_mul_f32_e32 v21, v15, v15
	v_fma_f32 v18, v8, v8, v18
	v_fma_f32 v19, v9, v9, v19
	v_fma_f32 v20, v12, v12, v20
	v_fma_f32 v21, v13, v13, v21
	v_add_f32_e32 v5, v18, v19
	v_mul_f32_e32 v22, v2, v2
	v_mul_f32_e32 v23, v3, v3
	v_add_f32_e32 v5, v20, v5
	v_fma_f32 v22, v0, v0, v22
	v_fma_f32 v23, v1, v1, v23
	v_add_f32_e32 v5, v21, v5
	v_add_f32_e32 v8, v8, v10
	v_add_f32_e32 v9, v9, v11
	v_add_f32_e32 v18, v22, v5
	v_add_f32_e32 v5, 0, v8
	v_add_f32_e32 v5, v9, v5
	v_add_f32_e32 v8, v12, v14
	v_add_f32_e32 v9, v13, v15
	v_add_f32_e32 v19, v23, v18
	v_add_f32_e32 v18, v22, v18
	v_add_f32_e32 v5, v8, v5
	v_mov_b32_e32 v20, v6
	v_mov_b32_e32 v21, v16
	v_mul_f32_e32 v18, v6, v6
	v_add_f32_e32 v5, v9, v5
	v_add_f32_e32 v0, v0, v2
	v_add_f32_e32 v1, v1, v3
	v_fma_f32 v20, v20, v20, v18
	v_fma_f32 v21, v21, v21, v18
	v_add_f32_e32 v22, v6, v16
	v_add_f32_e32 v23, v7, v17
	v_mul_f32_e32 v16, v6, v16
	v_mul_f32_e32 v17, v7, v17
	v_add_f32_e32 v0, v0, v5
	v_mov_b32_e32 v23, v17
	v_mul_f32_e32 v17, v4, v4
	v_add_f32_e32 v16, v1, v0
	v_mov_b32_e32 v20, v7
	v_mov_b32_e32 v5, v19
	v_add_f32_e32 v0, v22, v16
	v_add_f32_e32 v1, v23, v17
	v_add_f32_e32 v2, v20, v4
	v_add_f32_e32 v3, v21, v5
	s_nop 0
	v_add_f32_e32 v0, v0, v2
	v_add_f32_e32 v1, v1, v3
	ds_bpermute_b32 v2, v205, v0
	ds_bpermute_b32 v3, v205, v1
	s_waitcnt lgkmcnt(0)
	v_add_f32_e32 v0, v0, v2
	v_add_f32_e32 v1, v1, v3
	ds_bpermute_b32 v2, v206, v0
	ds_bpermute_b32 v3, v206, v1
	s_and_saveexec_b64 s[42:43], s[38:39]
	s_cbranch_execz .LBB0_217
	v_lshlrev_b64 v[4:5], 8, v[180:181]
	s_waitcnt lgkmcnt(0)
	v_add_f32_e32 v0, v0, v2
	v_add_f32_e32 v1, v1, v3
	v_lshl_add_u64 v[2:3], s[6:7], 0, v[4:5]
	v_lshl_add_u64 v[2:3], s[36:37], 3, v[2:3]
	global_store_dwordx2 v[2:3], v[0:1], off
